# all 20 K-loop MFMA blocks aligned to 8 bytes (s_nop padding on the loader side before the barrier), on top of trimmed block
# baseline (speedup 1.0000x reference)
; #define PG8_STAGE(bufoff, gbase, voff) do { _Pragma("unroll") for (int _i = 0; _i < 2; ++_i) \
;         __builtin_amdgcn_global_load_lds((const unsigned*)((const char*)(gbase) + (voff)[_i]), (PG8_LAS unsigned*)(lds + (bufoff) + ldsw + _i * 8192), 16, 0, 0); } while (0)
; #define PG8_LDA(dst, b, h) do { _Pragma("unroll") for (int m = 0; m < 4; ++m) _Pragma("unroll") for (int k = 0; k < 2; ++k) dst[m][k] = *(const PG8_LAS bf16x8*)(lds + PG8_SA(b, h) + aoff + m * 2048 + k * 1024); } while (0)
; #define PG8_LDB(dst, b, h) do { _Pragma("unroll") for (int n = 0; n < 2; ++n) _Pragma("unroll") for (int k = 0; k < 2; ++k) dst[n][k] = *(const PG8_LAS bf16x8*)(lds + PG8_SB(b, h) + boff + n * 2048 + k * 1024); } while (0)
; #define PG8_MMA(ai, bj, At, Bt) do { __builtin_amdgcn_s_setprio(1); _Pragma("unroll") for (int m = 0; m < 4; ++m) _Pragma("unroll") for (int n = 0; n < 2; ++n) _Pragma("unroll") for (int k = 0; k < 2; ++k) \
;         acc[ai][bj][m][n] = __builtin_amdgcn_mfma_f32_16x16x32_bf16(Bt[n][k], At[m][k], acc[ai][bj][m][n], 0, 0, 0); __builtin_amdgcn_s_setprio(0); } while (0)
; #define PG8_WAIT_V(n) asm volatile("s_waitcnt vmcnt(" #n ")" ::: "memory")
; #define PG8_BAR __builtin_amdgcn_s_barrier()
; template <class Epi, class Sched, bool ALIGN_EPI = false, bool SP2 = false>
; __device__ __forceinline__ void gemm_phase(PG8_LAS unsigned char* lds, const Gemm g, const Sched& S, const Epi& E) {
;     ...
;         for (int t = 0; t < nt; t += 2) {
;             const bool last = (t == nt - 2);
;             const char* a1 = cA + (size_t)(t + 1) * kstep;
;             const char* a2 = last ? nA : cA + (size_t)(t + 2) * kstep; const char* b2 = last ? nB : cB + (size_t)(t + 2) * kstep;
;             const char* a3 = a2 + kstep; const char* b3 = b2 + kstep;
;             if (last && has_next) S.a_ready(nxt);
;             if constexpr (SP2) {
;             PG8_LDB(B0, 0, 0); PG8_LDB(B1, 0, 1); PG8_SCHED; PG8_LDA(At, 0, 0); PG8_STAGE(PG8_SA(1, 1), a1 + hstep, voffA);
;             PG8_WAIT_V(8); PG8_WAIT_L(0); PG8_BAR; PG8_MMA(0, 0, At, B0); PG8_MMA(0, 1, At, B1); PG8_BAR; PG8_SCHED;
;             PG8_LDA(At, 0, 1); PG8_STAGE(PG8_SB(0, 0), b2, voffB); PG8_STAGE(PG8_SB(0, 1), b2 + hstep, voffB); PG8_STAGE(PG8_SA(0, 0), a2, voffA);
;             PG8_WAIT_V(8); PG8_WAIT_L(0); PG8_BAR; PG8_MMA(1, 0, At, B0); PG8_MMA(1, 1, At, B1); PG8_BAR; PG8_SCHED;
.LBB0_419:
	s_add_u32 s26, s48, 0xfff80080
	s_addc_u32 s27, s49, -1
	s_add_i32 s39, 0, 0x10000
	s_cmp_eq_u32 s17, 28
	s_cselect_b32 s29, s15, s27
	s_cselect_b32 s28, s30, s26
	s_cselect_b32 s27, s31, s16
	s_cselect_b32 s26, s34, s35
	s_add_i32 s41, 0, 0x14000
	v_add_u32_e32 v142, s39, v190
	v_add_u32_e32 v170, s41, v190
	ds_read_b128 v[130:133], v142
	ds_read_b128 v[134:137], v142 offset:1024
	ds_read_b128 v[138:141], v142 offset:2048
	ds_read_b128 v[142:145], v142 offset:3072
	ds_read_b128 v[146:149], v170
	ds_read_b128 v[150:153], v170 offset:1024
	ds_read_b128 v[178:181], v170 offset:2048
	ds_read_b128 v[182:185], v170 offset:3072
	v_lshl_add_u64 v[170:171], s[48:49], 0, v[176:177]
	s_add_i32 m0, s6, 0xc000
	ds_read_b128 v[186:189], v192
	ds_read_b128 v[194:197], v192 offset:1024
	ds_read_b128 v[198:201], v192 offset:2048
	ds_read_b128 v[202:205], v192 offset:3072
	ds_read_b128 v[206:209], v192 offset:4096
	ds_read_b128 v[220:223], v192 offset:5120
	ds_read_b128 v[224:227], v192 offset:6144
	ds_read_b128 v[228:231], v192 offset:7168
	global_load_lds_dwordx4 v[170:171], off
	v_lshl_add_u64 v[170:171], s[48:49], 0, v[174:175]
	s_add_i32 m0, s6, 0xe000
	s_nop 0
	global_load_lds_dwordx4 v[170:171], off
	s_waitcnt vmcnt(8)
	s_waitcnt lgkmcnt(0)
	s_nop 0
	s_setprio 1
	s_barrier
	v_mfma_f32_16x16x32_bf16 v[126:129], v[130:133], v[186:189], v[126:129]
	v_mfma_f32_16x16x32_bf16 v[122:125], v[138:141], v[186:189], v[122:125]
	v_mfma_f32_16x16x32_bf16 v[110:113], v[130:133], v[198:201], v[110:113]
	v_mfma_f32_16x16x32_bf16 v[106:109], v[138:141], v[198:201], v[106:109]
	v_mfma_f32_16x16x32_bf16 v[94:97], v[130:133], v[206:209], v[94:97]
	v_mfma_f32_16x16x32_bf16 v[90:93], v[138:141], v[206:209], v[90:93]
	v_mfma_f32_16x16x32_bf16 v[78:81], v[130:133], v[224:227], v[78:81]
	v_mfma_f32_16x16x32_bf16 v[74:77], v[138:141], v[224:227], v[74:77]
	v_mfma_f32_16x16x32_bf16 v[126:129], v[134:137], v[194:197], v[126:129]
	v_mfma_f32_16x16x32_bf16 v[122:125], v[142:145], v[194:197], v[122:125]
	v_mfma_f32_16x16x32_bf16 v[110:113], v[134:137], v[202:205], v[110:113]
	v_mfma_f32_16x16x32_bf16 v[106:109], v[142:145], v[202:205], v[106:109]
	v_mfma_f32_16x16x32_bf16 v[94:97], v[134:137], v[220:223], v[94:97]
	v_mfma_f32_16x16x32_bf16 v[90:93], v[142:145], v[220:223], v[90:93]
	v_mfma_f32_16x16x32_bf16 v[78:81], v[134:137], v[228:231], v[78:81]
	v_mfma_f32_16x16x32_bf16 v[74:77], v[142:145], v[228:231], v[74:77]
	v_mfma_f32_16x16x32_bf16 v[118:121], v[146:149], v[186:189], v[118:121]
	v_mfma_f32_16x16x32_bf16 v[114:117], v[178:181], v[186:189], v[114:117]
	v_mfma_f32_16x16x32_bf16 v[102:105], v[146:149], v[198:201], v[102:105]
	v_mfma_f32_16x16x32_bf16 v[98:101], v[178:181], v[198:201], v[98:101]
	v_mfma_f32_16x16x32_bf16 v[86:89], v[146:149], v[206:209], v[86:89]
	v_mfma_f32_16x16x32_bf16 v[82:85], v[178:181], v[206:209], v[82:85]
	v_mfma_f32_16x16x32_bf16 v[70:73], v[146:149], v[224:227], v[70:73]
	v_mfma_f32_16x16x32_bf16 v[66:69], v[178:181], v[224:227], v[66:69]
	v_mfma_f32_16x16x32_bf16 v[118:121], v[150:153], v[194:197], v[118:121]
	v_mfma_f32_16x16x32_bf16 v[114:117], v[182:185], v[194:197], v[114:117]
	v_mfma_f32_16x16x32_bf16 v[102:105], v[150:153], v[202:205], v[102:105]
	v_mfma_f32_16x16x32_bf16 v[98:101], v[182:185], v[202:205], v[98:101]
	v_mfma_f32_16x16x32_bf16 v[86:89], v[150:153], v[220:223], v[86:89]
	v_mfma_f32_16x16x32_bf16 v[82:85], v[182:185], v[220:223], v[82:85]
	v_mfma_f32_16x16x32_bf16 v[70:73], v[150:153], v[228:231], v[70:73]
	v_mfma_f32_16x16x32_bf16 v[66:69], v[182:185], v[228:231], v[66:69]
	s_barrier
	s_setprio 0
	s_add_i32 s39, s39, s5
	v_lshl_add_u64 v[170:171], s[26:27], 0, v[158:159]
	s_mov_b32 m0, s39
	ds_read_b128 v[186:189], v192 offset:16384
	ds_read_b128 v[194:197], v192 offset:17408
	ds_read_b128 v[198:201], v192 offset:18432
	ds_read_b128 v[202:205], v192 offset:19456
	ds_read_b128 v[206:209], v192 offset:20480
	ds_read_b128 v[220:223], v192 offset:21504
	ds_read_b128 v[224:227], v192 offset:22528
	ds_read_b128 v[228:231], v192 offset:23552
	global_load_lds_dwordx4 v[170:171], off
	s_add_i32 m0, s39, 0x2000
	s_add_u32 s50, s26, 0x80000
	v_lshl_add_u64 v[210:211], s[26:27], 0, v[154:155]
	s_addc_u32 s51, s27, 0
	s_add_i32 s39, s41, s5
	global_load_lds_dwordx4 v[210:211], off
	v_lshl_add_u64 v[232:233], s[50:51], 0, v[158:159]
	s_mov_b32 m0, s39
	v_lshl_add_u64 v[234:235], s[28:29], 0, v[156:157]
	global_load_lds_dwordx4 v[232:233], off
	v_lshl_add_u64 v[232:233], s[50:51], 0, v[154:155]
	s_add_i32 m0, s39, 0x2000
	s_nop 0
	global_load_lds_dwordx4 v[232:233], off
	v_lshl_add_u64 v[232:233], s[28:29], 0, v[172:173]
	s_mov_b32 m0, s6
	s_nop 0
	global_load_lds_dwordx4 v[232:233], off
	s_mov_b32 m0, s7
	s_nop 0
	global_load_lds_dwordx4 v[234:235], off
	s_waitcnt vmcnt(8)
	s_waitcnt lgkmcnt(0)
	s_setprio 1
	s_barrier
; #define PG8_STAGE(bufoff, gbase, voff) do { _Pragma("unroll") for (int _i = 0; _i < 2; ++_i) \
;         __builtin_amdgcn_global_load_lds((const unsigned*)((const char*)(gbase) + (voff)[_i]), (PG8_LAS unsigned*)(lds + (bufoff) + ldsw + _i * 8192), 16, 0, 0); } while (0)
; #define PG8_LDA(dst, b, h) do { _Pragma("unroll") for (int m = 0; m < 4; ++m) _Pragma("unroll") for (int k = 0; k < 2; ++k) dst[m][k] = *(const PG8_LAS bf16x8*)(lds + PG8_SA(b, h) + aoff + m * 2048 + k * 1024); } while (0)
; #define PG8_LDB(dst, b, h) do { _Pragma("unroll") for (int n = 0; n < 2; ++n) _Pragma("unroll") for (int k = 0; k < 2; ++k) dst[n][k] = *(const PG8_LAS bf16x8*)(lds + PG8_SB(b, h) + boff + n * 2048 + k * 1024); } while (0)
; #define PG8_MMA(ai, bj, At, Bt) do { __builtin_amdgcn_s_setprio(1); _Pragma("unroll") for (int m = 0; m < 4; ++m) _Pragma("unroll") for (int n = 0; n < 2; ++n) _Pragma("unroll") for (int k = 0; k < 2; ++k) \
;         acc[ai][bj][m][n] = __builtin_amdgcn_mfma_f32_16x16x32_bf16(Bt[n][k], At[m][k], acc[ai][bj][m][n], 0, 0, 0); __builtin_amdgcn_s_setprio(0); } while (0)
; #define PG8_WAIT_V(n) asm volatile("s_waitcnt vmcnt(" #n ")" ::: "memory")
; #define PG8_WAIT_L(n) asm volatile("s_waitcnt lgkmcnt(" #n ")" ::: "memory")
; #define PG8_BAR __builtin_amdgcn_s_barrier()
; #define PG8_SCHED __builtin_amdgcn_sched_barrier(0)
; template <class Epi, class Sched, bool ALIGN_EPI = false, bool SP2 = false>
; __device__ __forceinline__ void gemm_phase(PG8_LAS unsigned char* lds, const Gemm g, const Sched& S, const Epi& E) {
;     ...
;             PG8_WAIT_V(8); PG8_WAIT_L(0); PG8_BAR; PG8_MMA(1, 0, At, B0); PG8_MMA(1, 1, At, B1); PG8_BAR; PG8_SCHED;
;             PG8_LDB(B0, 1, 0); PG8_LDB(B1, 1, 1); PG8_SCHED; PG8_LDA(At, 1, 0); PG8_STAGE(PG8_SA(0, 1), a2 + hstep, voffA);
;             PG8_WAIT_V(8); PG8_WAIT_L(0); PG8_BAR; PG8_MMA(0, 0, At, B0); PG8_MMA(0, 1, At, B1); PG8_BAR; PG8_SCHED;
	v_mfma_f32_16x16x32_bf16 v[62:65], v[130:133], v[186:189], v[62:65]
	v_mfma_f32_16x16x32_bf16 v[58:61], v[138:141], v[186:189], v[58:61]
	v_mfma_f32_16x16x32_bf16 v[46:49], v[130:133], v[198:201], v[46:49]
	v_mfma_f32_16x16x32_bf16 v[42:45], v[138:141], v[198:201], v[42:45]
	v_mfma_f32_16x16x32_bf16 v[30:33], v[130:133], v[206:209], v[30:33]
	v_mfma_f32_16x16x32_bf16 v[26:29], v[138:141], v[206:209], v[26:29]
	v_mfma_f32_16x16x32_bf16 v[14:17], v[130:133], v[224:227], v[14:17]
	v_mfma_f32_16x16x32_bf16 v[10:13], v[138:141], v[224:227], v[10:13]
	v_mfma_f32_16x16x32_bf16 v[62:65], v[134:137], v[194:197], v[62:65]
	v_mfma_f32_16x16x32_bf16 v[58:61], v[142:145], v[194:197], v[58:61]
	v_mfma_f32_16x16x32_bf16 v[46:49], v[134:137], v[202:205], v[46:49]
	v_mfma_f32_16x16x32_bf16 v[42:45], v[142:145], v[202:205], v[42:45]
	v_mfma_f32_16x16x32_bf16 v[30:33], v[134:137], v[220:223], v[30:33]
	v_mfma_f32_16x16x32_bf16 v[26:29], v[142:145], v[220:223], v[26:29]
	v_mfma_f32_16x16x32_bf16 v[14:17], v[134:137], v[228:231], v[14:17]
	v_mfma_f32_16x16x32_bf16 v[10:13], v[142:145], v[228:231], v[10:13]
	v_mfma_f32_16x16x32_bf16 v[54:57], v[146:149], v[186:189], v[54:57]
	v_mfma_f32_16x16x32_bf16 v[50:53], v[178:181], v[186:189], v[50:53]
	v_mfma_f32_16x16x32_bf16 v[38:41], v[146:149], v[198:201], v[38:41]
	v_mfma_f32_16x16x32_bf16 v[34:37], v[178:181], v[198:201], v[34:37]
	v_mfma_f32_16x16x32_bf16 v[22:25], v[146:149], v[206:209], v[22:25]
	v_mfma_f32_16x16x32_bf16 v[18:21], v[178:181], v[206:209], v[18:21]
	v_mfma_f32_16x16x32_bf16 v[6:9], v[146:149], v[224:227], v[6:9]
	v_mfma_f32_16x16x32_bf16 v[2:5], v[178:181], v[224:227], v[2:5]
	v_mfma_f32_16x16x32_bf16 v[54:57], v[150:153], v[194:197], v[54:57]
	v_mfma_f32_16x16x32_bf16 v[50:53], v[182:185], v[194:197], v[50:53]
	v_mfma_f32_16x16x32_bf16 v[38:41], v[150:153], v[202:205], v[38:41]
	v_mfma_f32_16x16x32_bf16 v[34:37], v[182:185], v[202:205], v[34:37]
	v_mfma_f32_16x16x32_bf16 v[22:25], v[150:153], v[220:223], v[22:25]
	v_mfma_f32_16x16x32_bf16 v[18:21], v[182:185], v[220:223], v[18:21]
	v_mfma_f32_16x16x32_bf16 v[6:9], v[150:153], v[228:231], v[6:9]
	v_mfma_f32_16x16x32_bf16 v[2:5], v[182:185], v[228:231], v[2:5]
	s_barrier
	s_setprio 0
	s_add_i32 s39, 0, 0x18000
	s_add_i32 s41, 0, 0x1c000
	v_add_u32_e32 v142, s39, v190
	v_add_u32_e32 v182, s41, v190
	ds_read_b128 v[130:133], v142
	ds_read_b128 v[134:137], v142 offset:1024
	ds_read_b128 v[138:141], v142 offset:2048
	ds_read_b128 v[142:145], v142 offset:3072
	ds_read_b128 v[146:149], v182
	ds_read_b128 v[150:153], v182 offset:1024
	ds_read_b128 v[178:181], v182 offset:2048
	ds_read_b128 v[182:185], v182 offset:3072
	s_add_u32 s28, s28, 0x80000
	s_addc_u32 s29, s29, 0
	s_mov_b32 m0, s8
	v_lshl_add_u64 v[236:237], s[28:29], 0, v[172:173]
	ds_read_b128 v[186:189], v192 offset:32768
	ds_read_b128 v[194:197], v192 offset:33792
	ds_read_b128 v[198:201], v192 offset:34816
	ds_read_b128 v[202:205], v192 offset:35840
	ds_read_b128 v[206:209], v192 offset:36864
	ds_read_b128 v[220:223], v192 offset:37888
	ds_read_b128 v[224:227], v192 offset:38912
	ds_read_b128 v[228:231], v192 offset:39936
	global_load_lds_dwordx4 v[236:237], off
	v_lshl_add_u64 v[236:237], s[28:29], 0, v[156:157]
	s_mov_b32 m0, s9
	s_nop 0
	global_load_lds_dwordx4 v[236:237], off
	s_waitcnt vmcnt(8)
	s_waitcnt lgkmcnt(0)
	s_setprio 1
	s_barrier
	v_mfma_f32_16x16x32_bf16 v[126:129], v[130:133], v[186:189], v[126:129]
	v_mfma_f32_16x16x32_bf16 v[122:125], v[138:141], v[186:189], v[122:125]
	v_mfma_f32_16x16x32_bf16 v[110:113], v[130:133], v[198:201], v[110:113]
	v_mfma_f32_16x16x32_bf16 v[106:109], v[138:141], v[198:201], v[106:109]
	v_mfma_f32_16x16x32_bf16 v[94:97], v[130:133], v[206:209], v[94:97]
	v_mfma_f32_16x16x32_bf16 v[90:93], v[138:141], v[206:209], v[90:93]
	v_mfma_f32_16x16x32_bf16 v[78:81], v[130:133], v[224:227], v[78:81]
	v_mfma_f32_16x16x32_bf16 v[74:77], v[138:141], v[224:227], v[74:77]
	v_mfma_f32_16x16x32_bf16 v[126:129], v[134:137], v[194:197], v[126:129]
	v_mfma_f32_16x16x32_bf16 v[122:125], v[142:145], v[194:197], v[122:125]
	v_mfma_f32_16x16x32_bf16 v[110:113], v[134:137], v[202:205], v[110:113]
	v_mfma_f32_16x16x32_bf16 v[106:109], v[142:145], v[202:205], v[106:109]
	v_mfma_f32_16x16x32_bf16 v[94:97], v[134:137], v[220:223], v[94:97]
	v_mfma_f32_16x16x32_bf16 v[90:93], v[142:145], v[220:223], v[90:93]
	v_mfma_f32_16x16x32_bf16 v[78:81], v[134:137], v[228:231], v[78:81]
	v_mfma_f32_16x16x32_bf16 v[74:77], v[142:145], v[228:231], v[74:77]
	v_mfma_f32_16x16x32_bf16 v[118:121], v[146:149], v[186:189], v[118:121]
	v_mfma_f32_16x16x32_bf16 v[114:117], v[178:181], v[186:189], v[114:117]
	v_mfma_f32_16x16x32_bf16 v[102:105], v[146:149], v[198:201], v[102:105]
	v_mfma_f32_16x16x32_bf16 v[98:101], v[178:181], v[198:201], v[98:101]
	v_mfma_f32_16x16x32_bf16 v[86:89], v[146:149], v[206:209], v[86:89]
	v_mfma_f32_16x16x32_bf16 v[82:85], v[178:181], v[206:209], v[82:85]
	v_mfma_f32_16x16x32_bf16 v[70:73], v[146:149], v[224:227], v[70:73]
	v_mfma_f32_16x16x32_bf16 v[66:69], v[178:181], v[224:227], v[66:69]
	v_mfma_f32_16x16x32_bf16 v[118:121], v[150:153], v[194:197], v[118:121]
	v_mfma_f32_16x16x32_bf16 v[114:117], v[182:185], v[194:197], v[114:117]
	v_mfma_f32_16x16x32_bf16 v[102:105], v[150:153], v[202:205], v[102:105]
	v_mfma_f32_16x16x32_bf16 v[98:101], v[182:185], v[202:205], v[98:101]
	v_mfma_f32_16x16x32_bf16 v[86:89], v[150:153], v[220:223], v[86:89]
	v_mfma_f32_16x16x32_bf16 v[82:85], v[182:185], v[220:223], v[82:85]
	v_mfma_f32_16x16x32_bf16 v[70:73], v[150:153], v[228:231], v[70:73]
	v_mfma_f32_16x16x32_bf16 v[66:69], v[182:185], v[228:231], v[66:69]
	s_barrier
; #define PG8_STAGE(bufoff, gbase, voff) do { _Pragma("unroll") for (int _i = 0; _i < 2; ++_i) \
;         __builtin_amdgcn_global_load_lds((const unsigned*)((const char*)(gbase) + (voff)[_i]), (PG8_LAS unsigned*)(lds + (bufoff) + ldsw + _i * 8192), 16, 0, 0); } while (0)
; #define PG8_LDA(dst, b, h) do { _Pragma("unroll") for (int m = 0; m < 4; ++m) _Pragma("unroll") for (int k = 0; k < 2; ++k) dst[m][k] = *(const PG8_LAS bf16x8*)(lds + PG8_SA(b, h) + aoff + m * 2048 + k * 1024); } while (0)
; #define PG8_MMA(ai, bj, At, Bt) do { __builtin_amdgcn_s_setprio(1); _Pragma("unroll") for (int m = 0; m < 4; ++m) _Pragma("unroll") for (int n = 0; n < 2; ++n) _Pragma("unroll") for (int k = 0; k < 2; ++k) \
;         acc[ai][bj][m][n] = __builtin_amdgcn_mfma_f32_16x16x32_bf16(Bt[n][k], At[m][k], acc[ai][bj][m][n], 0, 0, 0); __builtin_amdgcn_s_setprio(0); } while (0)
; #define PG8_WAIT_V(n) asm volatile("s_waitcnt vmcnt(" #n ")" ::: "memory")
; #define PG8_WAIT_L(n) asm volatile("s_waitcnt lgkmcnt(" #n ")" ::: "memory")
; #define PG8_BAR __builtin_amdgcn_s_barrier()
; #define PG8_SCHED __builtin_amdgcn_sched_barrier(0)
; template <class Epi, class Sched, bool ALIGN_EPI = false, bool SP2 = false>
; __device__ __forceinline__ void gemm_phase(PG8_LAS unsigned char* lds, const Gemm g, const Sched& S, const Epi& E) {
;     ...
;             PG8_WAIT_V(8); PG8_WAIT_L(0); PG8_BAR; PG8_MMA(0, 0, At, B0); PG8_MMA(0, 1, At, B1); PG8_BAR; PG8_SCHED;
;             PG8_LDA(At, 1, 1); PG8_STAGE(PG8_SB(1, 0), b3, voffB); PG8_STAGE(PG8_SB(1, 1), b3 + hstep, voffB); PG8_STAGE(PG8_SA(1, 0), a3, voffA);
;             PG8_WAIT_V(8); PG8_WAIT_L(0); PG8_BAR; PG8_MMA(1, 0, At, B0); PG8_MMA(1, 1, At, B1); PG8_BAR; PG8_SCHED;
	s_setprio 0
	s_add_i32 s28, s39, s5
	v_lshl_add_u64 v[170:171], v[170:171], 0, s[96:97]
	s_mov_b32 m0, s28
	ds_read_b128 v[186:189], v192 offset:49152
	ds_read_b128 v[194:197], v192 offset:50176
	ds_read_b128 v[198:201], v192 offset:51200
	ds_read_b128 v[202:205], v192 offset:52224
	ds_read_b128 v[206:209], v192 offset:53248
	ds_read_b128 v[220:223], v192 offset:54272
	ds_read_b128 v[224:227], v192 offset:55296
	ds_read_b128 v[228:231], v192 offset:56320
	global_load_lds_dwordx4 v[170:171], off
	s_add_i32 m0, s28, 0x2000
	s_add_u32 s26, s26, 0x80080
	v_lshl_add_u64 v[170:171], v[210:211], 0, s[96:97]
	s_addc_u32 s27, s27, 0
	s_add_i32 s28, s41, s5
	global_load_lds_dwordx4 v[170:171], off
	v_lshl_add_u64 v[170:171], s[26:27], 0, v[158:159]
	s_mov_b32 m0, s28
	s_nop 0
	global_load_lds_dwordx4 v[170:171], off
	v_lshl_add_u64 v[170:171], s[26:27], 0, v[154:155]
	s_add_i32 m0, s28, 0x2000
	s_nop 0
	global_load_lds_dwordx4 v[170:171], off
	v_lshl_add_u64 v[170:171], v[232:233], 0, s[96:97]
	s_mov_b32 m0, s10
	s_nop 0
	global_load_lds_dwordx4 v[170:171], off
	v_lshl_add_u64 v[170:171], v[234:235], 0, s[96:97]
	s_mov_b32 m0, s11
	s_nop 0
	global_load_lds_dwordx4 v[170:171], off
	s_waitcnt vmcnt(8)
	s_waitcnt lgkmcnt(0)
	s_nop 0
	s_setprio 1
	s_barrier
	v_mfma_f32_16x16x32_bf16 v[62:65], v[130:133], v[186:189], v[62:65]
	v_mfma_f32_16x16x32_bf16 v[58:61], v[138:141], v[186:189], v[58:61]
	v_mfma_f32_16x16x32_bf16 v[46:49], v[130:133], v[198:201], v[46:49]
	v_mfma_f32_16x16x32_bf16 v[42:45], v[138:141], v[198:201], v[42:45]
	v_mfma_f32_16x16x32_bf16 v[30:33], v[130:133], v[206:209], v[30:33]
	v_mfma_f32_16x16x32_bf16 v[26:29], v[138:141], v[206:209], v[26:29]
	v_mfma_f32_16x16x32_bf16 v[14:17], v[130:133], v[224:227], v[14:17]
	v_mfma_f32_16x16x32_bf16 v[10:13], v[138:141], v[224:227], v[10:13]
	v_mfma_f32_16x16x32_bf16 v[62:65], v[134:137], v[194:197], v[62:65]
	v_mfma_f32_16x16x32_bf16 v[58:61], v[142:145], v[194:197], v[58:61]
	v_mfma_f32_16x16x32_bf16 v[46:49], v[134:137], v[202:205], v[46:49]
	v_mfma_f32_16x16x32_bf16 v[42:45], v[142:145], v[202:205], v[42:45]
	v_mfma_f32_16x16x32_bf16 v[30:33], v[134:137], v[220:223], v[30:33]
	v_mfma_f32_16x16x32_bf16 v[26:29], v[142:145], v[220:223], v[26:29]
	v_mfma_f32_16x16x32_bf16 v[14:17], v[134:137], v[228:231], v[14:17]
	v_mfma_f32_16x16x32_bf16 v[10:13], v[142:145], v[228:231], v[10:13]
	v_mfma_f32_16x16x32_bf16 v[54:57], v[146:149], v[186:189], v[54:57]
	v_mfma_f32_16x16x32_bf16 v[50:53], v[178:181], v[186:189], v[50:53]
	v_mfma_f32_16x16x32_bf16 v[38:41], v[146:149], v[198:201], v[38:41]
	v_mfma_f32_16x16x32_bf16 v[34:37], v[178:181], v[198:201], v[34:37]
	v_mfma_f32_16x16x32_bf16 v[22:25], v[146:149], v[206:209], v[22:25]
	v_mfma_f32_16x16x32_bf16 v[18:21], v[178:181], v[206:209], v[18:21]
	v_mfma_f32_16x16x32_bf16 v[6:9], v[146:149], v[224:227], v[6:9]
	v_mfma_f32_16x16x32_bf16 v[2:5], v[178:181], v[224:227], v[2:5]
	v_mfma_f32_16x16x32_bf16 v[54:57], v[150:153], v[194:197], v[54:57]
	v_mfma_f32_16x16x32_bf16 v[50:53], v[182:185], v[194:197], v[50:53]
	v_mfma_f32_16x16x32_bf16 v[38:41], v[150:153], v[202:205], v[38:41]
	v_mfma_f32_16x16x32_bf16 v[34:37], v[182:185], v[202:205], v[34:37]
	v_mfma_f32_16x16x32_bf16 v[22:25], v[150:153], v[220:223], v[22:25]
	v_mfma_f32_16x16x32_bf16 v[18:21], v[182:185], v[220:223], v[18:21]
	v_mfma_f32_16x16x32_bf16 v[6:9], v[150:153], v[228:231], v[6:9]
	v_mfma_f32_16x16x32_bf16 v[2:5], v[182:185], v[228:231], v[2:5]
	s_barrier
	s_setprio 0
	s_add_i32 s17, s17, 2
	s_add_u32 s35, s35, 0x100
	s_addc_u32 s16, s16, 0
	s_add_u32 s48, s48, 0x100
	s_addc_u32 s49, s49, 0
	s_cmp_gt_u32 s17, 29
	s_cbranch_scc0 .LBB0_419
	s_and_b64 vcc, exec, s[36:37]
	s_cbranch_vccz .LBB0_422
	s_barrier

; #define PG8_STAGE(bufoff, gbase, voff) do { _Pragma("unroll") for (int _i = 0; _i < 2; ++_i) \
;         __builtin_amdgcn_global_load_lds((const unsigned*)((const char*)(gbase) + (voff)[_i]), (PG8_LAS unsigned*)(lds + (bufoff) + ldsw + _i * 8192), 16, 0, 0); } while (0)
; #define PG8_LDA(dst, b, h) do { _Pragma("unroll") for (int m = 0; m < 4; ++m) _Pragma("unroll") for (int k = 0; k < 2; ++k) dst[m][k] = *(const PG8_LAS bf16x8*)(lds + PG8_SA(b, h) + aoff + m * 2048 + k * 1024); } while (0)
; #define PG8_LDB(dst, b, h) do { _Pragma("unroll") for (int n = 0; n < 2; ++n) _Pragma("unroll") for (int k = 0; k < 2; ++k) dst[n][k] = *(const PG8_LAS bf16x8*)(lds + PG8_SB(b, h) + boff + n * 2048 + k * 1024); } while (0)
; #define PG8_MMA(ai, bj, At, Bt) do { __builtin_amdgcn_s_setprio(1); _Pragma("unroll") for (int m = 0; m < 4; ++m) _Pragma("unroll") for (int n = 0; n < 2; ++n) _Pragma("unroll") for (int k = 0; k < 2; ++k) \
;         acc[ai][bj][m][n] = __builtin_amdgcn_mfma_f32_16x16x32_bf16(Bt[n][k], At[m][k], acc[ai][bj][m][n], 0, 0, 0); __builtin_amdgcn_s_setprio(0); } while (0)
; #define PG8_WAIT_V(n) asm volatile("s_waitcnt vmcnt(" #n ")" ::: "memory")
; #define PG8_BAR __builtin_amdgcn_s_barrier()
; template <class Epi, class Sched, bool ALIGN_EPI = false, bool SP2 = false>
; __device__ __forceinline__ void gemm_phase(PG8_LAS unsigned char* lds, const Gemm g, const Sched& S, const Epi& E) {
;     ...
;         for (int t = 0; t < nt; t += 2) {
;             const bool last = (t == nt - 2);
;             const char* a1 = cA + (size_t)(t + 1) * kstep;
;             const char* a2 = last ? nA : cA + (size_t)(t + 2) * kstep; const char* b2 = last ? nB : cB + (size_t)(t + 2) * kstep;
;             const char* a3 = a2 + kstep; const char* b3 = b2 + kstep;
;             if (last && has_next) S.a_ready(nxt);
;             if constexpr (SP2) {
;             PG8_LDB(B0, 0, 0); PG8_LDB(B1, 0, 1); PG8_SCHED; PG8_LDA(At, 0, 0); PG8_STAGE(PG8_SA(1, 1), a1 + hstep, voffA);
;             PG8_WAIT_V(8); PG8_WAIT_L(0); PG8_BAR; PG8_MMA(0, 0, At, B0); PG8_MMA(0, 1, At, B1); PG8_BAR; PG8_SCHED;
;             PG8_LDA(At, 0, 1); PG8_STAGE(PG8_SB(0, 0), b2, voffB); PG8_STAGE(PG8_SB(0, 1), b2 + hstep, voffB); PG8_STAGE(PG8_SA(0, 0), a2, voffA);
;             PG8_WAIT_V(8); PG8_WAIT_L(0); PG8_BAR; PG8_MMA(1, 0, At, B0); PG8_MMA(1, 1, At, B1); PG8_BAR; PG8_SCHED;
.LBB0_530:
	s_add_i32 s21, s17, 2
	s_add_u32 s23, s24, 0xfff00080
	s_addc_u32 s26, s25, -1
	s_add_i32 s30, 0, 0x10000
	s_cmp_eq_u32 s14, s17
	s_cselect_b32 s29, s55, s26
	s_cselect_b32 s28, s54, s23
	s_cselect_b32 s27, s57, s16
	s_cselect_b32 s26, s56, s15
	s_add_i32 s17, 0, 0x14000
	v_add_u32_e32 v142, s30, v190
	v_add_u32_e32 v170, s17, v190
	ds_read_b128 v[130:133], v142
	ds_read_b128 v[134:137], v142 offset:1024
	ds_read_b128 v[138:141], v142 offset:2048
	ds_read_b128 v[142:145], v142 offset:3072
	ds_read_b128 v[146:149], v170
	ds_read_b128 v[150:153], v170 offset:1024
	ds_read_b128 v[178:181], v170 offset:2048
	ds_read_b128 v[182:185], v170 offset:3072
	v_lshl_add_u64 v[170:171], s[24:25], 0, v[176:177]
	s_add_i32 m0, s35, 0xc000
	ds_read_b128 v[186:189], v192
	ds_read_b128 v[194:197], v192 offset:1024
	ds_read_b128 v[198:201], v192 offset:2048
	ds_read_b128 v[202:205], v192 offset:3072
	ds_read_b128 v[206:209], v192 offset:4096
	ds_read_b128 v[220:223], v192 offset:5120
	ds_read_b128 v[224:227], v192 offset:6144
	ds_read_b128 v[228:231], v192 offset:7168
	global_load_lds_dwordx4 v[170:171], off
	v_lshl_add_u64 v[170:171], s[24:25], 0, v[174:175]
	s_add_i32 m0, s35, 0xe000
	s_nop 0
	global_load_lds_dwordx4 v[170:171], off
	s_waitcnt vmcnt(8)
	s_waitcnt lgkmcnt(0)
	s_nop 0
	s_setprio 1
	s_barrier
	v_mfma_f32_16x16x32_bf16 v[126:129], v[130:133], v[186:189], v[126:129]
	v_mfma_f32_16x16x32_bf16 v[122:125], v[138:141], v[186:189], v[122:125]
	v_mfma_f32_16x16x32_bf16 v[118:121], v[130:133], v[198:201], v[118:121]
	v_mfma_f32_16x16x32_bf16 v[114:117], v[138:141], v[198:201], v[114:117]
	v_mfma_f32_16x16x32_bf16 v[102:105], v[130:133], v[206:209], v[102:105]
	v_mfma_f32_16x16x32_bf16 v[94:97], v[138:141], v[206:209], v[94:97]
	v_mfma_f32_16x16x32_bf16 v[86:89], v[130:133], v[224:227], v[86:89]
	v_mfma_f32_16x16x32_bf16 v[78:81], v[138:141], v[224:227], v[78:81]
	v_mfma_f32_16x16x32_bf16 v[126:129], v[134:137], v[194:197], v[126:129]
	v_mfma_f32_16x16x32_bf16 v[122:125], v[142:145], v[194:197], v[122:125]
	v_mfma_f32_16x16x32_bf16 v[118:121], v[134:137], v[202:205], v[118:121]
	v_mfma_f32_16x16x32_bf16 v[114:117], v[142:145], v[202:205], v[114:117]
	v_mfma_f32_16x16x32_bf16 v[102:105], v[134:137], v[220:223], v[102:105]
	v_mfma_f32_16x16x32_bf16 v[94:97], v[142:145], v[220:223], v[94:97]
	v_mfma_f32_16x16x32_bf16 v[86:89], v[134:137], v[228:231], v[86:89]
	v_mfma_f32_16x16x32_bf16 v[78:81], v[142:145], v[228:231], v[78:81]
	v_mfma_f32_16x16x32_bf16 v[110:113], v[146:149], v[186:189], v[110:113]
	v_mfma_f32_16x16x32_bf16 v[106:109], v[178:181], v[186:189], v[106:109]
	v_mfma_f32_16x16x32_bf16 v[98:101], v[146:149], v[198:201], v[98:101]
	v_mfma_f32_16x16x32_bf16 v[90:93], v[178:181], v[198:201], v[90:93]
	v_mfma_f32_16x16x32_bf16 v[82:85], v[146:149], v[206:209], v[82:85]
	v_mfma_f32_16x16x32_bf16 v[74:77], v[178:181], v[206:209], v[74:77]
	v_mfma_f32_16x16x32_bf16 v[70:73], v[146:149], v[224:227], v[70:73]
	v_mfma_f32_16x16x32_bf16 v[66:69], v[178:181], v[224:227], v[66:69]
	v_mfma_f32_16x16x32_bf16 v[110:113], v[150:153], v[194:197], v[110:113]
	v_mfma_f32_16x16x32_bf16 v[106:109], v[182:185], v[194:197], v[106:109]
	v_mfma_f32_16x16x32_bf16 v[98:101], v[150:153], v[202:205], v[98:101]
	v_mfma_f32_16x16x32_bf16 v[90:93], v[182:185], v[202:205], v[90:93]
	v_mfma_f32_16x16x32_bf16 v[82:85], v[150:153], v[220:223], v[82:85]
	v_mfma_f32_16x16x32_bf16 v[74:77], v[182:185], v[220:223], v[74:77]
	v_mfma_f32_16x16x32_bf16 v[70:73], v[150:153], v[228:231], v[70:73]
	v_mfma_f32_16x16x32_bf16 v[66:69], v[182:185], v[228:231], v[66:69]
	s_barrier
	s_setprio 0
	s_add_i32 s23, s30, s34
	v_lshl_add_u64 v[170:171], s[26:27], 0, v[158:159]
	s_mov_b32 m0, s23
	ds_read_b128 v[186:189], v192 offset:16384
	ds_read_b128 v[194:197], v192 offset:17408
	ds_read_b128 v[198:201], v192 offset:18432
	ds_read_b128 v[202:205], v192 offset:19456
	ds_read_b128 v[206:209], v192 offset:20480
	ds_read_b128 v[220:223], v192 offset:21504
	ds_read_b128 v[224:227], v192 offset:22528
	ds_read_b128 v[228:231], v192 offset:23552
	global_load_lds_dwordx4 v[170:171], off
	s_add_i32 m0, s23, 0x2000
	s_add_u32 s58, s26, 0x100000
	v_lshl_add_u64 v[210:211], s[26:27], 0, v[172:173]
	s_addc_u32 s59, s27, 0
	s_add_i32 s17, s17, s34
	global_load_lds_dwordx4 v[210:211], off
	v_lshl_add_u64 v[232:233], s[58:59], 0, v[158:159]
	s_mov_b32 m0, s17
	v_lshl_add_u64 v[234:235], s[28:29], 0, v[156:157]
	global_load_lds_dwordx4 v[232:233], off
	v_lshl_add_u64 v[232:233], s[58:59], 0, v[172:173]
	s_add_i32 m0, s17, 0x2000
	s_nop 0
	global_load_lds_dwordx4 v[232:233], off
	v_lshl_add_u64 v[232:233], s[28:29], 0, v[154:155]
	s_mov_b32 m0, s35
	s_nop 0
	global_load_lds_dwordx4 v[232:233], off
	s_mov_b32 m0, s4
	s_nop 0
	global_load_lds_dwordx4 v[234:235], off
	s_waitcnt vmcnt(8)
	s_waitcnt lgkmcnt(0)
	s_setprio 1
	s_barrier
; #define PG8_STAGE(bufoff, gbase, voff) do { _Pragma("unroll") for (int _i = 0; _i < 2; ++_i) \
;         __builtin_amdgcn_global_load_lds((const unsigned*)((const char*)(gbase) + (voff)[_i]), (PG8_LAS unsigned*)(lds + (bufoff) + ldsw + _i * 8192), 16, 0, 0); } while (0)
; #define PG8_LDA(dst, b, h) do { _Pragma("unroll") for (int m = 0; m < 4; ++m) _Pragma("unroll") for (int k = 0; k < 2; ++k) dst[m][k] = *(const PG8_LAS bf16x8*)(lds + PG8_SA(b, h) + aoff + m * 2048 + k * 1024); } while (0)
; #define PG8_LDB(dst, b, h) do { _Pragma("unroll") for (int n = 0; n < 2; ++n) _Pragma("unroll") for (int k = 0; k < 2; ++k) dst[n][k] = *(const PG8_LAS bf16x8*)(lds + PG8_SB(b, h) + boff + n * 2048 + k * 1024); } while (0)
; #define PG8_MMA(ai, bj, At, Bt) do { __builtin_amdgcn_s_setprio(1); _Pragma("unroll") for (int m = 0; m < 4; ++m) _Pragma("unroll") for (int n = 0; n < 2; ++n) _Pragma("unroll") for (int k = 0; k < 2; ++k) \
;         acc[ai][bj][m][n] = __builtin_amdgcn_mfma_f32_16x16x32_bf16(Bt[n][k], At[m][k], acc[ai][bj][m][n], 0, 0, 0); __builtin_amdgcn_s_setprio(0); } while (0)
; #define PG8_WAIT_V(n) asm volatile("s_waitcnt vmcnt(" #n ")" ::: "memory")
; #define PG8_WAIT_L(n) asm volatile("s_waitcnt lgkmcnt(" #n ")" ::: "memory")
; #define PG8_BAR __builtin_amdgcn_s_barrier()
; #define PG8_SCHED __builtin_amdgcn_sched_barrier(0)
; template <class Epi, class Sched, bool ALIGN_EPI = false, bool SP2 = false>
; __device__ __forceinline__ void gemm_phase(PG8_LAS unsigned char* lds, const Gemm g, const Sched& S, const Epi& E) {
;     ...
;             PG8_WAIT_V(8); PG8_WAIT_L(0); PG8_BAR; PG8_MMA(1, 0, At, B0); PG8_MMA(1, 1, At, B1); PG8_BAR; PG8_SCHED;
;             PG8_LDB(B0, 1, 0); PG8_LDB(B1, 1, 1); PG8_SCHED; PG8_LDA(At, 1, 0); PG8_STAGE(PG8_SA(0, 1), a2 + hstep, voffA);
;             PG8_WAIT_V(8); PG8_WAIT_L(0); PG8_BAR; PG8_MMA(0, 0, At, B0); PG8_MMA(0, 1, At, B1); PG8_BAR; PG8_SCHED;
	v_mfma_f32_16x16x32_bf16 v[62:65], v[130:133], v[186:189], v[62:65]
	v_mfma_f32_16x16x32_bf16 v[58:61], v[138:141], v[186:189], v[58:61]
	v_mfma_f32_16x16x32_bf16 v[54:57], v[130:133], v[198:201], v[54:57]
	v_mfma_f32_16x16x32_bf16 v[46:49], v[138:141], v[198:201], v[46:49]
	v_mfma_f32_16x16x32_bf16 v[38:41], v[130:133], v[206:209], v[38:41]
	v_mfma_f32_16x16x32_bf16 v[30:33], v[138:141], v[206:209], v[30:33]
	v_mfma_f32_16x16x32_bf16 v[22:25], v[130:133], v[224:227], v[22:25]
	v_mfma_f32_16x16x32_bf16 v[14:17], v[138:141], v[224:227], v[14:17]
	v_mfma_f32_16x16x32_bf16 v[62:65], v[134:137], v[194:197], v[62:65]
	v_mfma_f32_16x16x32_bf16 v[58:61], v[142:145], v[194:197], v[58:61]
	v_mfma_f32_16x16x32_bf16 v[54:57], v[134:137], v[202:205], v[54:57]
	v_mfma_f32_16x16x32_bf16 v[46:49], v[142:145], v[202:205], v[46:49]
	v_mfma_f32_16x16x32_bf16 v[38:41], v[134:137], v[220:223], v[38:41]
	v_mfma_f32_16x16x32_bf16 v[30:33], v[142:145], v[220:223], v[30:33]
	v_mfma_f32_16x16x32_bf16 v[22:25], v[134:137], v[228:231], v[22:25]
	v_mfma_f32_16x16x32_bf16 v[14:17], v[142:145], v[228:231], v[14:17]
	v_mfma_f32_16x16x32_bf16 v[50:53], v[146:149], v[186:189], v[50:53]
	v_mfma_f32_16x16x32_bf16 v[42:45], v[178:181], v[186:189], v[42:45]
	v_mfma_f32_16x16x32_bf16 v[34:37], v[146:149], v[198:201], v[34:37]
	v_mfma_f32_16x16x32_bf16 v[26:29], v[178:181], v[198:201], v[26:29]
	v_mfma_f32_16x16x32_bf16 v[18:21], v[146:149], v[206:209], v[18:21]
	v_mfma_f32_16x16x32_bf16 v[10:13], v[178:181], v[206:209], v[10:13]
	v_mfma_f32_16x16x32_bf16 v[6:9], v[146:149], v[224:227], v[6:9]
	v_mfma_f32_16x16x32_bf16 v[2:5], v[178:181], v[224:227], v[2:5]
	v_mfma_f32_16x16x32_bf16 v[50:53], v[150:153], v[194:197], v[50:53]
	v_mfma_f32_16x16x32_bf16 v[42:45], v[182:185], v[194:197], v[42:45]
	v_mfma_f32_16x16x32_bf16 v[34:37], v[150:153], v[202:205], v[34:37]
	v_mfma_f32_16x16x32_bf16 v[26:29], v[182:185], v[202:205], v[26:29]
	v_mfma_f32_16x16x32_bf16 v[18:21], v[150:153], v[220:223], v[18:21]
	v_mfma_f32_16x16x32_bf16 v[10:13], v[182:185], v[220:223], v[10:13]
	v_mfma_f32_16x16x32_bf16 v[6:9], v[150:153], v[228:231], v[6:9]
	v_mfma_f32_16x16x32_bf16 v[2:5], v[182:185], v[228:231], v[2:5]
	s_barrier
	s_setprio 0
	s_add_i32 s17, 0, 0x18000
	s_add_i32 s23, 0, 0x1c000
	v_add_u32_e32 v142, s17, v190
	v_add_u32_e32 v182, s23, v190
	ds_read_b128 v[130:133], v142
	ds_read_b128 v[134:137], v142 offset:1024
	ds_read_b128 v[138:141], v142 offset:2048
	ds_read_b128 v[142:145], v142 offset:3072
	ds_read_b128 v[146:149], v182
	ds_read_b128 v[150:153], v182 offset:1024
	ds_read_b128 v[178:181], v182 offset:2048
	ds_read_b128 v[182:185], v182 offset:3072
	s_add_u32 s28, s28, 0x100000
	s_addc_u32 s29, s29, 0
	s_mov_b32 m0, s5
	v_lshl_add_u64 v[236:237], s[28:29], 0, v[154:155]
	ds_read_b128 v[186:189], v192 offset:32768
	ds_read_b128 v[194:197], v192 offset:33792
	ds_read_b128 v[198:201], v192 offset:34816
	ds_read_b128 v[202:205], v192 offset:35840
	ds_read_b128 v[206:209], v192 offset:36864
	ds_read_b128 v[220:223], v192 offset:37888
	ds_read_b128 v[224:227], v192 offset:38912
	ds_read_b128 v[228:231], v192 offset:39936
	global_load_lds_dwordx4 v[236:237], off
	v_lshl_add_u64 v[236:237], s[28:29], 0, v[156:157]
	s_mov_b32 m0, s6
	s_nop 0
	global_load_lds_dwordx4 v[236:237], off
	s_waitcnt vmcnt(8)
	s_waitcnt lgkmcnt(0)
	s_setprio 1
	s_barrier
	v_mfma_f32_16x16x32_bf16 v[126:129], v[130:133], v[186:189], v[126:129]
	v_mfma_f32_16x16x32_bf16 v[122:125], v[138:141], v[186:189], v[122:125]
	v_mfma_f32_16x16x32_bf16 v[118:121], v[130:133], v[198:201], v[118:121]
	v_mfma_f32_16x16x32_bf16 v[114:117], v[138:141], v[198:201], v[114:117]
	v_mfma_f32_16x16x32_bf16 v[102:105], v[130:133], v[206:209], v[102:105]
	v_mfma_f32_16x16x32_bf16 v[94:97], v[138:141], v[206:209], v[94:97]
	v_mfma_f32_16x16x32_bf16 v[86:89], v[130:133], v[224:227], v[86:89]
	v_mfma_f32_16x16x32_bf16 v[78:81], v[138:141], v[224:227], v[78:81]
	v_mfma_f32_16x16x32_bf16 v[126:129], v[134:137], v[194:197], v[126:129]
	v_mfma_f32_16x16x32_bf16 v[122:125], v[142:145], v[194:197], v[122:125]
	v_mfma_f32_16x16x32_bf16 v[118:121], v[134:137], v[202:205], v[118:121]
	v_mfma_f32_16x16x32_bf16 v[114:117], v[142:145], v[202:205], v[114:117]
	v_mfma_f32_16x16x32_bf16 v[102:105], v[134:137], v[220:223], v[102:105]
	v_mfma_f32_16x16x32_bf16 v[94:97], v[142:145], v[220:223], v[94:97]
	v_mfma_f32_16x16x32_bf16 v[86:89], v[134:137], v[228:231], v[86:89]
	v_mfma_f32_16x16x32_bf16 v[78:81], v[142:145], v[228:231], v[78:81]
	v_mfma_f32_16x16x32_bf16 v[110:113], v[146:149], v[186:189], v[110:113]
	v_mfma_f32_16x16x32_bf16 v[106:109], v[178:181], v[186:189], v[106:109]
	v_mfma_f32_16x16x32_bf16 v[98:101], v[146:149], v[198:201], v[98:101]
	v_mfma_f32_16x16x32_bf16 v[90:93], v[178:181], v[198:201], v[90:93]
	v_mfma_f32_16x16x32_bf16 v[82:85], v[146:149], v[206:209], v[82:85]
	v_mfma_f32_16x16x32_bf16 v[74:77], v[178:181], v[206:209], v[74:77]
	v_mfma_f32_16x16x32_bf16 v[70:73], v[146:149], v[224:227], v[70:73]
	v_mfma_f32_16x16x32_bf16 v[66:69], v[178:181], v[224:227], v[66:69]
	v_mfma_f32_16x16x32_bf16 v[110:113], v[150:153], v[194:197], v[110:113]
	v_mfma_f32_16x16x32_bf16 v[106:109], v[182:185], v[194:197], v[106:109]
	v_mfma_f32_16x16x32_bf16 v[98:101], v[150:153], v[202:205], v[98:101]
	v_mfma_f32_16x16x32_bf16 v[90:93], v[182:185], v[202:205], v[90:93]
	v_mfma_f32_16x16x32_bf16 v[82:85], v[150:153], v[220:223], v[82:85]
	v_mfma_f32_16x16x32_bf16 v[74:77], v[182:185], v[220:223], v[74:77]
	v_mfma_f32_16x16x32_bf16 v[70:73], v[150:153], v[228:231], v[70:73]
	v_mfma_f32_16x16x32_bf16 v[66:69], v[182:185], v[228:231], v[66:69]
	s_barrier
; #define PG8_STAGE(bufoff, gbase, voff) do { _Pragma("unroll") for (int _i = 0; _i < 2; ++_i) \
;         __builtin_amdgcn_global_load_lds((const unsigned*)((const char*)(gbase) + (voff)[_i]), (PG8_LAS unsigned*)(lds + (bufoff) + ldsw + _i * 8192), 16, 0, 0); } while (0)
; #define PG8_LDA(dst, b, h) do { _Pragma("unroll") for (int m = 0; m < 4; ++m) _Pragma("unroll") for (int k = 0; k < 2; ++k) dst[m][k] = *(const PG8_LAS bf16x8*)(lds + PG8_SA(b, h) + aoff + m * 2048 + k * 1024); } while (0)
; #define PG8_MMA(ai, bj, At, Bt) do { __builtin_amdgcn_s_setprio(1); _Pragma("unroll") for (int m = 0; m < 4; ++m) _Pragma("unroll") for (int n = 0; n < 2; ++n) _Pragma("unroll") for (int k = 0; k < 2; ++k) \
;         acc[ai][bj][m][n] = __builtin_amdgcn_mfma_f32_16x16x32_bf16(Bt[n][k], At[m][k], acc[ai][bj][m][n], 0, 0, 0); __builtin_amdgcn_s_setprio(0); } while (0)
; #define PG8_WAIT_V(n) asm volatile("s_waitcnt vmcnt(" #n ")" ::: "memory")
; #define PG8_WAIT_L(n) asm volatile("s_waitcnt lgkmcnt(" #n ")" ::: "memory")
; #define PG8_BAR __builtin_amdgcn_s_barrier()
; #define PG8_SCHED __builtin_amdgcn_sched_barrier(0)
; template <class Epi, class Sched, bool ALIGN_EPI = false, bool SP2 = false>
; __device__ __forceinline__ void gemm_phase(PG8_LAS unsigned char* lds, const Gemm g, const Sched& S, const Epi& E) {
;     ...
;             PG8_WAIT_V(8); PG8_WAIT_L(0); PG8_BAR; PG8_MMA(0, 0, At, B0); PG8_MMA(0, 1, At, B1); PG8_BAR; PG8_SCHED;
;             PG8_LDA(At, 1, 1); PG8_STAGE(PG8_SB(1, 0), b3, voffB); PG8_STAGE(PG8_SB(1, 1), b3 + hstep, voffB); PG8_STAGE(PG8_SA(1, 0), a3, voffA);
;             PG8_WAIT_V(8); PG8_WAIT_L(0); PG8_BAR; PG8_MMA(1, 0, At, B0); PG8_MMA(1, 1, At, B1); PG8_BAR; PG8_SCHED;
	s_setprio 0
	s_add_i32 s17, s17, s34
	v_lshl_add_u64 v[170:171], v[170:171], 0, s[96:97]
	s_mov_b32 m0, s17
	ds_read_b128 v[186:189], v192 offset:49152
	ds_read_b128 v[194:197], v192 offset:50176
	ds_read_b128 v[198:201], v192 offset:51200
	ds_read_b128 v[202:205], v192 offset:52224
	ds_read_b128 v[206:209], v192 offset:53248
	ds_read_b128 v[220:223], v192 offset:54272
	ds_read_b128 v[224:227], v192 offset:55296
	ds_read_b128 v[228:231], v192 offset:56320
	global_load_lds_dwordx4 v[170:171], off
	s_add_i32 m0, s17, 0x2000
	s_add_u32 s26, s26, 0x100080
	v_lshl_add_u64 v[170:171], v[210:211], 0, s[96:97]
	s_addc_u32 s27, s27, 0
	s_add_i32 s17, s23, s34
	global_load_lds_dwordx4 v[170:171], off
	v_lshl_add_u64 v[170:171], s[26:27], 0, v[158:159]
	s_mov_b32 m0, s17
	s_nop 0
	global_load_lds_dwordx4 v[170:171], off
	v_lshl_add_u64 v[170:171], s[26:27], 0, v[172:173]
	s_add_i32 m0, s17, 0x2000
	s_nop 0
	global_load_lds_dwordx4 v[170:171], off
	v_lshl_add_u64 v[170:171], v[232:233], 0, s[96:97]
	s_mov_b32 m0, s9
	s_nop 0
	global_load_lds_dwordx4 v[170:171], off
	v_lshl_add_u64 v[170:171], v[234:235], 0, s[96:97]
	s_mov_b32 m0, s10
	s_nop 0
	global_load_lds_dwordx4 v[170:171], off
	s_waitcnt vmcnt(8)
	s_waitcnt lgkmcnt(0)
	s_nop 0
	s_setprio 1
	s_barrier
	v_mfma_f32_16x16x32_bf16 v[62:65], v[130:133], v[186:189], v[62:65]
	v_mfma_f32_16x16x32_bf16 v[58:61], v[138:141], v[186:189], v[58:61]
	v_mfma_f32_16x16x32_bf16 v[54:57], v[130:133], v[198:201], v[54:57]
	v_mfma_f32_16x16x32_bf16 v[46:49], v[138:141], v[198:201], v[46:49]
	v_mfma_f32_16x16x32_bf16 v[38:41], v[130:133], v[206:209], v[38:41]
	v_mfma_f32_16x16x32_bf16 v[30:33], v[138:141], v[206:209], v[30:33]
	v_mfma_f32_16x16x32_bf16 v[22:25], v[130:133], v[224:227], v[22:25]
	v_mfma_f32_16x16x32_bf16 v[14:17], v[138:141], v[224:227], v[14:17]
	v_mfma_f32_16x16x32_bf16 v[62:65], v[134:137], v[194:197], v[62:65]
	v_mfma_f32_16x16x32_bf16 v[58:61], v[142:145], v[194:197], v[58:61]
	v_mfma_f32_16x16x32_bf16 v[54:57], v[134:137], v[202:205], v[54:57]
	v_mfma_f32_16x16x32_bf16 v[46:49], v[142:145], v[202:205], v[46:49]
	v_mfma_f32_16x16x32_bf16 v[38:41], v[134:137], v[220:223], v[38:41]
	v_mfma_f32_16x16x32_bf16 v[30:33], v[142:145], v[220:223], v[30:33]
	v_mfma_f32_16x16x32_bf16 v[22:25], v[134:137], v[228:231], v[22:25]
	v_mfma_f32_16x16x32_bf16 v[14:17], v[142:145], v[228:231], v[14:17]
	v_mfma_f32_16x16x32_bf16 v[50:53], v[146:149], v[186:189], v[50:53]
	v_mfma_f32_16x16x32_bf16 v[42:45], v[178:181], v[186:189], v[42:45]
	v_mfma_f32_16x16x32_bf16 v[34:37], v[146:149], v[198:201], v[34:37]
	v_mfma_f32_16x16x32_bf16 v[26:29], v[178:181], v[198:201], v[26:29]
	v_mfma_f32_16x16x32_bf16 v[18:21], v[146:149], v[206:209], v[18:21]
	v_mfma_f32_16x16x32_bf16 v[10:13], v[178:181], v[206:209], v[10:13]
	v_mfma_f32_16x16x32_bf16 v[6:9], v[146:149], v[224:227], v[6:9]
	v_mfma_f32_16x16x32_bf16 v[2:5], v[178:181], v[224:227], v[2:5]
	v_mfma_f32_16x16x32_bf16 v[50:53], v[150:153], v[194:197], v[50:53]
	v_mfma_f32_16x16x32_bf16 v[42:45], v[182:185], v[194:197], v[42:45]
	v_mfma_f32_16x16x32_bf16 v[34:37], v[150:153], v[202:205], v[34:37]
	v_mfma_f32_16x16x32_bf16 v[26:29], v[182:185], v[202:205], v[26:29]
	v_mfma_f32_16x16x32_bf16 v[18:21], v[150:153], v[220:223], v[18:21]
	v_mfma_f32_16x16x32_bf16 v[10:13], v[182:185], v[220:223], v[10:13]
	v_mfma_f32_16x16x32_bf16 v[6:9], v[150:153], v[228:231], v[6:9]
	v_mfma_f32_16x16x32_bf16 v[2:5], v[182:185], v[228:231], v[2:5]
	s_barrier
	s_setprio 0
	s_add_u32 s15, s15, 0x100
	s_addc_u32 s16, s16, 0
	s_add_u32 s24, s24, 0x100
	s_addc_u32 s25, s25, 0
	s_cmp_ge_i32 s21, s13
	s_mov_b32 s17, s21
	s_cbranch_scc0 .LBB0_530
	s_and_b64 vcc, exec, s[46:47]
	s_cbranch_vccz .LBB0_533
	s_barrier

; #define PG8_STAGE(bufoff, gbase, voff) do { _Pragma("unroll") for (int _i = 0; _i < 2; ++_i) \
;         __builtin_amdgcn_global_load_lds((const unsigned*)((const char*)(gbase) + (voff)[_i]), (PG8_LAS unsigned*)(lds + (bufoff) + ldsw + _i * 8192), 16, 0, 0); } while (0)
; #define PG8_LDA(dst, b, h) do { _Pragma("unroll") for (int m = 0; m < 4; ++m) _Pragma("unroll") for (int k = 0; k < 2; ++k) dst[m][k] = *(const PG8_LAS bf16x8*)(lds + PG8_SA(b, h) + aoff + m * 2048 + k * 1024); } while (0)
; #define PG8_LDB(dst, b, h) do { _Pragma("unroll") for (int n = 0; n < 2; ++n) _Pragma("unroll") for (int k = 0; k < 2; ++k) dst[n][k] = *(const PG8_LAS bf16x8*)(lds + PG8_SB(b, h) + boff + n * 2048 + k * 1024); } while (0)
; #define PG8_MMA(ai, bj, At, Bt) do { __builtin_amdgcn_s_setprio(1); _Pragma("unroll") for (int m = 0; m < 4; ++m) _Pragma("unroll") for (int n = 0; n < 2; ++n) _Pragma("unroll") for (int k = 0; k < 2; ++k) \
;         acc[ai][bj][m][n] = __builtin_amdgcn_mfma_f32_16x16x32_bf16(Bt[n][k], At[m][k], acc[ai][bj][m][n], 0, 0, 0); __builtin_amdgcn_s_setprio(0); } while (0)
; #define PG8_WAIT_V(n) asm volatile("s_waitcnt vmcnt(" #n ")" ::: "memory")
; #define PG8_BAR __builtin_amdgcn_s_barrier()
; template <class Epi, class Sched, bool ALIGN_EPI = false, bool SP2 = false>
; __device__ __forceinline__ void gemm_phase(PG8_LAS unsigned char* lds, const Gemm g, const Sched& S, const Epi& E) {
;     ...
;         for (int t = 0; t < nt; t += 2) {
;             const bool last = (t == nt - 2);
;             const char* a1 = cA + (size_t)(t + 1) * kstep;
;             const char* a2 = last ? nA : cA + (size_t)(t + 2) * kstep; const char* b2 = last ? nB : cB + (size_t)(t + 2) * kstep;
;             const char* a3 = a2 + kstep; const char* b3 = b2 + kstep;
;             if (last && has_next) S.a_ready(nxt);
;             if constexpr (SP2) {
;             PG8_LDB(B0, 0, 0); PG8_LDB(B1, 0, 1); PG8_SCHED; PG8_LDA(At, 0, 0); PG8_STAGE(PG8_SA(1, 1), a1 + hstep, voffA);
;             PG8_WAIT_V(8); PG8_WAIT_L(0); PG8_BAR; PG8_MMA(0, 0, At, B0); PG8_MMA(0, 1, At, B1); PG8_BAR; PG8_SCHED;
;             PG8_LDA(At, 0, 1); PG8_STAGE(PG8_SB(0, 0), b2, voffB); PG8_STAGE(PG8_SB(0, 1), b2 + hstep, voffB); PG8_STAGE(PG8_SA(0, 0), a2, voffA);
;             PG8_WAIT_V(8); PG8_WAIT_L(0); PG8_BAR; PG8_MMA(1, 0, At, B0); PG8_MMA(1, 1, At, B1); PG8_BAR; PG8_SCHED;
.LBB0_710:
	s_add_u32 s22, vcc_lo, 0xfff00080
	s_addc_u32 s23, vcc_hi, -1
	s_add_i32 s68, 0, 0x10000
	s_cmp_eq_u32 s65, 60
	s_cselect_b32 s25, s30, s23
	s_cselect_b32 s24, s31, s22
	s_cselect_b32 s23, s61, s17
	s_cselect_b32 s22, s63, s16
	s_add_i32 s70, 0, 0x14000
	v_add_u32_e32 v70, s68, v220
	v_add_u32_e32 v170, s70, v220
	ds_read_b128 v[50:53], v70
	ds_read_b128 v[54:57], v70 offset:1024
	ds_read_b128 v[66:69], v70 offset:2048
	ds_read_b128 v[70:73], v70 offset:3072
	ds_read_b128 v[74:77], v170
	ds_read_b128 v[86:89], v170 offset:1024
	ds_read_b128 v[154:157], v170 offset:2048
	ds_read_b128 v[188:191], v170 offset:3072
	v_lshl_add_u64 v[170:171], vcc, 0, v[186:187]
	s_add_i32 m0, s10, 0xc000
	ds_read_b128 v[192:195], v222
	ds_read_b128 v[196:199], v222 offset:1024
	ds_read_b128 v[200:203], v222 offset:2048
	ds_read_b128 v[204:207], v222 offset:3072
	ds_read_b128 v[224:227], v222 offset:4096
	ds_read_b128 v[228:231], v222 offset:5120
	ds_read_b128 v[232:235], v222 offset:6144
	ds_read_b128 v[236:239], v222 offset:7168
	global_load_lds_dwordx4 v[170:171], off
	v_lshl_add_u64 v[170:171], vcc, 0, v[184:185]
	s_add_i32 m0, s10, 0xe000
	s_nop 0
	global_load_lds_dwordx4 v[170:171], off
	s_waitcnt vmcnt(8)
	s_waitcnt lgkmcnt(0)
	s_nop 0
	s_setprio 1
	s_barrier
	v_mfma_f32_16x16x32_bf16 v[142:145], v[50:53], v[192:195], v[142:145]
	v_mfma_f32_16x16x32_bf16 v[130:133], v[66:69], v[192:195], v[130:133]
	v_mfma_f32_16x16x32_bf16 v[138:141], v[50:53], v[200:203], v[138:141]
	v_mfma_f32_16x16x32_bf16 v[126:129], v[66:69], v[200:203], v[126:129]
	v_mfma_f32_16x16x32_bf16 v[118:121], v[50:53], v[224:227], v[118:121]
	v_mfma_f32_16x16x32_bf16 v[110:113], v[66:69], v[224:227], v[110:113]
	v_mfma_f32_16x16x32_bf16 v[98:101], v[50:53], v[232:235], v[98:101]
	v_mfma_f32_16x16x32_bf16 v[94:97], v[66:69], v[232:235], v[94:97]
	v_mfma_f32_16x16x32_bf16 v[142:145], v[54:57], v[196:199], v[142:145]
	v_mfma_f32_16x16x32_bf16 v[130:133], v[70:73], v[196:199], v[130:133]
	v_mfma_f32_16x16x32_bf16 v[138:141], v[54:57], v[204:207], v[138:141]
	v_mfma_f32_16x16x32_bf16 v[126:129], v[70:73], v[204:207], v[126:129]
	v_mfma_f32_16x16x32_bf16 v[118:121], v[54:57], v[228:231], v[118:121]
	v_mfma_f32_16x16x32_bf16 v[110:113], v[70:73], v[228:231], v[110:113]
	v_mfma_f32_16x16x32_bf16 v[98:101], v[54:57], v[236:239], v[98:101]
	v_mfma_f32_16x16x32_bf16 v[94:97], v[70:73], v[236:239], v[94:97]
	v_mfma_f32_16x16x32_bf16 v[150:153], v[74:77], v[192:195], v[150:153]
	v_mfma_f32_16x16x32_bf16 v[146:149], v[154:157], v[192:195], v[146:149]
	v_mfma_f32_16x16x32_bf16 v[134:137], v[74:77], v[200:203], v[134:137]
	v_mfma_f32_16x16x32_bf16 v[122:125], v[154:157], v[200:203], v[122:125]
	v_mfma_f32_16x16x32_bf16 v[114:117], v[74:77], v[224:227], v[114:117]
	v_mfma_f32_16x16x32_bf16 v[106:109], v[154:157], v[224:227], v[106:109]
	v_mfma_f32_16x16x32_bf16 v[102:105], v[74:77], v[232:235], v[102:105]
	v_mfma_f32_16x16x32_bf16 v[90:93], v[154:157], v[232:235], v[90:93]
	v_mfma_f32_16x16x32_bf16 v[150:153], v[86:89], v[196:199], v[150:153]
	v_mfma_f32_16x16x32_bf16 v[146:149], v[188:191], v[196:199], v[146:149]
	v_mfma_f32_16x16x32_bf16 v[134:137], v[86:89], v[204:207], v[134:137]
	v_mfma_f32_16x16x32_bf16 v[122:125], v[188:191], v[204:207], v[122:125]
	v_mfma_f32_16x16x32_bf16 v[114:117], v[86:89], v[228:231], v[114:117]
	v_mfma_f32_16x16x32_bf16 v[106:109], v[188:191], v[228:231], v[106:109]
	v_mfma_f32_16x16x32_bf16 v[102:105], v[86:89], v[236:239], v[102:105]
	v_mfma_f32_16x16x32_bf16 v[90:93], v[188:191], v[236:239], v[90:93]
	s_barrier
	s_setprio 0
	s_add_i32 s68, s68, s9
	v_lshl_add_u64 v[170:171], s[22:23], 0, v[158:159]
	s_mov_b32 m0, s68
	ds_read_b128 v[192:195], v222 offset:16384
	ds_read_b128 v[196:199], v222 offset:17408
	ds_read_b128 v[200:203], v222 offset:18432
	ds_read_b128 v[204:207], v222 offset:19456
	ds_read_b128 v[224:227], v222 offset:20480
	ds_read_b128 v[228:231], v222 offset:21504
	ds_read_b128 v[232:235], v222 offset:22528
	ds_read_b128 v[236:239], v222 offset:23552
	global_load_lds_dwordx4 v[170:171], off
	s_add_i32 m0, s68, 0x2000
	s_add_u32 s68, s22, 0x100000
	v_lshl_add_u64 v[208:209], s[22:23], 0, v[172:173]
	s_addc_u32 s69, s23, 0
	s_add_i32 s70, s70, s9
	global_load_lds_dwordx4 v[208:209], off
	v_lshl_add_u64 v[210:211], s[68:69], 0, v[158:159]
	s_mov_b32 m0, s70
	v_lshl_add_u64 v[244:245], s[24:25], 0, v[174:175]
	global_load_lds_dwordx4 v[210:211], off
	v_lshl_add_u64 v[210:211], s[68:69], 0, v[172:173]
	s_add_i32 m0, s70, 0x2000
	s_nop 0
	global_load_lds_dwordx4 v[210:211], off
	v_lshl_add_u64 v[210:211], s[24:25], 0, v[176:177]
	s_mov_b32 m0, s10
	s_nop 0
	global_load_lds_dwordx4 v[210:211], off
	s_mov_b32 m0, s11
	s_nop 0
	global_load_lds_dwordx4 v[244:245], off
	s_waitcnt vmcnt(8)
	s_waitcnt lgkmcnt(0)
	s_setprio 1
	s_barrier
; #define PG8_STAGE(bufoff, gbase, voff) do { _Pragma("unroll") for (int _i = 0; _i < 2; ++_i) \
;         __builtin_amdgcn_global_load_lds((const unsigned*)((const char*)(gbase) + (voff)[_i]), (PG8_LAS unsigned*)(lds + (bufoff) + ldsw + _i * 8192), 16, 0, 0); } while (0)
; #define PG8_LDA(dst, b, h) do { _Pragma("unroll") for (int m = 0; m < 4; ++m) _Pragma("unroll") for (int k = 0; k < 2; ++k) dst[m][k] = *(const PG8_LAS bf16x8*)(lds + PG8_SA(b, h) + aoff + m * 2048 + k * 1024); } while (0)
; #define PG8_LDB(dst, b, h) do { _Pragma("unroll") for (int n = 0; n < 2; ++n) _Pragma("unroll") for (int k = 0; k < 2; ++k) dst[n][k] = *(const PG8_LAS bf16x8*)(lds + PG8_SB(b, h) + boff + n * 2048 + k * 1024); } while (0)
; #define PG8_MMA(ai, bj, At, Bt) do { __builtin_amdgcn_s_setprio(1); _Pragma("unroll") for (int m = 0; m < 4; ++m) _Pragma("unroll") for (int n = 0; n < 2; ++n) _Pragma("unroll") for (int k = 0; k < 2; ++k) \
;         acc[ai][bj][m][n] = __builtin_amdgcn_mfma_f32_16x16x32_bf16(Bt[n][k], At[m][k], acc[ai][bj][m][n], 0, 0, 0); __builtin_amdgcn_s_setprio(0); } while (0)
; #define PG8_WAIT_V(n) asm volatile("s_waitcnt vmcnt(" #n ")" ::: "memory")
; #define PG8_WAIT_L(n) asm volatile("s_waitcnt lgkmcnt(" #n ")" ::: "memory")
; #define PG8_BAR __builtin_amdgcn_s_barrier()
; #define PG8_SCHED __builtin_amdgcn_sched_barrier(0)
; template <class Epi, class Sched, bool ALIGN_EPI = false, bool SP2 = false>
; __device__ __forceinline__ void gemm_phase(PG8_LAS unsigned char* lds, const Gemm g, const Sched& S, const Epi& E) {
;     ...
;             PG8_WAIT_V(8); PG8_WAIT_L(0); PG8_BAR; PG8_MMA(1, 0, At, B0); PG8_MMA(1, 1, At, B1); PG8_BAR; PG8_SCHED;
;             PG8_LDB(B0, 1, 0); PG8_LDB(B1, 1, 1); PG8_SCHED; PG8_LDA(At, 1, 0); PG8_STAGE(PG8_SA(0, 1), a2 + hstep, voffA);
;             PG8_WAIT_V(8); PG8_WAIT_L(0); PG8_BAR; PG8_MMA(0, 0, At, B0); PG8_MMA(0, 1, At, B1); PG8_BAR; PG8_SCHED;
	v_mfma_f32_16x16x32_bf16 v[62:65], v[50:53], v[192:195], v[62:65]
	v_mfma_f32_16x16x32_bf16 v[42:45], v[66:69], v[192:195], v[42:45]
	v_mfma_f32_16x16x32_bf16 v[58:61], v[50:53], v[200:203], v[58:61]
	v_mfma_f32_16x16x32_bf16 v[38:41], v[66:69], v[200:203], v[38:41]
	v_mfma_f32_16x16x32_bf16 v[30:33], v[50:53], v[224:227], v[30:33]
	v_mfma_f32_16x16x32_bf16 v[22:25], v[66:69], v[224:227], v[22:25]
	v_mfma_f32_16x16x32_bf16 v[10:13], v[50:53], v[232:235], v[10:13]
	v_mfma_f32_16x16x32_bf16 v[6:9], v[66:69], v[232:235], v[6:9]
	v_mfma_f32_16x16x32_bf16 v[62:65], v[54:57], v[196:199], v[62:65]
	v_mfma_f32_16x16x32_bf16 v[42:45], v[70:73], v[196:199], v[42:45]
	v_mfma_f32_16x16x32_bf16 v[58:61], v[54:57], v[204:207], v[58:61]
	v_mfma_f32_16x16x32_bf16 v[38:41], v[70:73], v[204:207], v[38:41]
	v_mfma_f32_16x16x32_bf16 v[30:33], v[54:57], v[228:231], v[30:33]
	v_mfma_f32_16x16x32_bf16 v[22:25], v[70:73], v[228:231], v[22:25]
	v_mfma_f32_16x16x32_bf16 v[10:13], v[54:57], v[236:239], v[10:13]
	v_mfma_f32_16x16x32_bf16 v[6:9], v[70:73], v[236:239], v[6:9]
	v_mfma_f32_16x16x32_bf16 v[46:49], v[74:77], v[200:203], v[46:49]
	v_mfma_f32_16x16x32_bf16 v[34:37], v[154:157], v[200:203], v[34:37]
	v_mfma_f32_16x16x32_bf16 v[26:29], v[74:77], v[224:227], v[26:29]
	v_mfma_f32_16x16x32_bf16 v[18:21], v[154:157], v[224:227], v[18:21]
	v_mfma_f32_16x16x32_bf16 v[14:17], v[74:77], v[232:235], v[14:17]
	v_mfma_f32_16x16x32_bf16 v[2:5], v[154:157], v[232:235], v[2:5]
	v_mfma_f32_16x16x32_bf16 v[50:53], v[74:77], v[192:195], v[82:85]
	v_mfma_f32_16x16x32_bf16 v[54:57], v[154:157], v[192:195], v[78:81]
	v_mfma_f32_16x16x32_bf16 v[46:49], v[86:89], v[204:207], v[46:49]
	v_mfma_f32_16x16x32_bf16 v[34:37], v[188:191], v[204:207], v[34:37]
	v_mfma_f32_16x16x32_bf16 v[26:29], v[86:89], v[228:231], v[26:29]
	v_mfma_f32_16x16x32_bf16 v[18:21], v[188:191], v[228:231], v[18:21]
	v_mfma_f32_16x16x32_bf16 v[14:17], v[86:89], v[236:239], v[14:17]
	v_mfma_f32_16x16x32_bf16 v[2:5], v[188:191], v[236:239], v[2:5]
	v_mfma_f32_16x16x32_bf16 v[50:53], v[86:89], v[196:199], v[50:53]
	v_mfma_f32_16x16x32_bf16 v[54:57], v[188:191], v[196:199], v[54:57]
	s_barrier
	s_setprio 0
	s_add_i32 s68, 0, 0x18000
	s_add_i32 s69, 0, 0x1c000
	v_add_u32_e32 v78, s68, v220
	v_add_u32_e32 v82, s69, v220
	ds_read_b128 v[66:69], v78
	ds_read_b128 v[70:73], v78 offset:1024
	ds_read_b128 v[74:77], v78 offset:2048
	ds_read_b128 v[78:81], v78 offset:3072
	ds_read_b128 v[86:89], v82
	ds_read_b128 v[154:157], v82 offset:1024
	ds_read_b128 v[188:191], v82 offset:2048
	ds_read_b128 v[192:195], v82 offset:3072
	s_add_u32 s24, s24, 0x100000
	s_addc_u32 s25, s25, 0
	s_mov_b32 m0, s12
	v_lshl_add_u64 v[240:241], s[24:25], 0, v[176:177]
	ds_read_b128 v[82:85], v222 offset:32768
	ds_read_b128 v[196:199], v222 offset:33792
	ds_read_b128 v[200:203], v222 offset:34816
	ds_read_b128 v[204:207], v222 offset:35840
	ds_read_b128 v[224:227], v222 offset:36864
	ds_read_b128 v[228:231], v222 offset:37888
	ds_read_b128 v[232:235], v222 offset:38912
	ds_read_b128 v[236:239], v222 offset:39936
	global_load_lds_dwordx4 v[240:241], off
	v_lshl_add_u64 v[240:241], s[24:25], 0, v[174:175]
	s_mov_b32 m0, s13
	s_nop 0
	global_load_lds_dwordx4 v[240:241], off
	s_waitcnt vmcnt(8)
	s_waitcnt lgkmcnt(0)
	s_setprio 1
	s_barrier
	v_mfma_f32_16x16x32_bf16 v[142:145], v[66:69], v[82:85], v[142:145]
	v_mfma_f32_16x16x32_bf16 v[130:133], v[74:77], v[82:85], v[130:133]
	v_mfma_f32_16x16x32_bf16 v[138:141], v[66:69], v[200:203], v[138:141]
	v_mfma_f32_16x16x32_bf16 v[126:129], v[74:77], v[200:203], v[126:129]
	v_mfma_f32_16x16x32_bf16 v[118:121], v[66:69], v[224:227], v[118:121]
	v_mfma_f32_16x16x32_bf16 v[110:113], v[74:77], v[224:227], v[110:113]
	v_mfma_f32_16x16x32_bf16 v[98:101], v[66:69], v[232:235], v[98:101]
	v_mfma_f32_16x16x32_bf16 v[94:97], v[74:77], v[232:235], v[94:97]
	v_mfma_f32_16x16x32_bf16 v[142:145], v[70:73], v[196:199], v[142:145]
	v_mfma_f32_16x16x32_bf16 v[130:133], v[78:81], v[196:199], v[130:133]
	v_mfma_f32_16x16x32_bf16 v[138:141], v[70:73], v[204:207], v[138:141]
	v_mfma_f32_16x16x32_bf16 v[126:129], v[78:81], v[204:207], v[126:129]
	v_mfma_f32_16x16x32_bf16 v[118:121], v[70:73], v[228:231], v[118:121]
	v_mfma_f32_16x16x32_bf16 v[110:113], v[78:81], v[228:231], v[110:113]
	v_mfma_f32_16x16x32_bf16 v[98:101], v[70:73], v[236:239], v[98:101]
	v_mfma_f32_16x16x32_bf16 v[94:97], v[78:81], v[236:239], v[94:97]
	v_mfma_f32_16x16x32_bf16 v[150:153], v[86:89], v[82:85], v[150:153]
	v_mfma_f32_16x16x32_bf16 v[82:85], v[188:191], v[82:85], v[146:149]
	v_mfma_f32_16x16x32_bf16 v[146:149], v[192:195], v[196:199], v[82:85]
	v_mfma_f32_16x16x32_bf16 v[82:85], v[86:89], v[200:203], v[134:137]
	v_mfma_f32_16x16x32_bf16 v[134:137], v[154:157], v[204:207], v[82:85]
	v_mfma_f32_16x16x32_bf16 v[82:85], v[188:191], v[200:203], v[122:125]
	v_mfma_f32_16x16x32_bf16 v[122:125], v[192:195], v[204:207], v[82:85]
	v_mfma_f32_16x16x32_bf16 v[82:85], v[86:89], v[224:227], v[114:117]
	v_mfma_f32_16x16x32_bf16 v[114:117], v[154:157], v[228:231], v[82:85]
	v_mfma_f32_16x16x32_bf16 v[82:85], v[188:191], v[224:227], v[106:109]
	v_mfma_f32_16x16x32_bf16 v[106:109], v[192:195], v[228:231], v[82:85]
	v_mfma_f32_16x16x32_bf16 v[82:85], v[86:89], v[232:235], v[102:105]
	v_mfma_f32_16x16x32_bf16 v[102:105], v[154:157], v[236:239], v[82:85]
	v_mfma_f32_16x16x32_bf16 v[82:85], v[188:191], v[232:235], v[90:93]
	v_mfma_f32_16x16x32_bf16 v[150:153], v[154:157], v[196:199], v[150:153]
	v_mfma_f32_16x16x32_bf16 v[90:93], v[192:195], v[236:239], v[82:85]
	s_barrier
; #define PG8_STAGE(bufoff, gbase, voff) do { _Pragma("unroll") for (int _i = 0; _i < 2; ++_i) \
;         __builtin_amdgcn_global_load_lds((const unsigned*)((const char*)(gbase) + (voff)[_i]), (PG8_LAS unsigned*)(lds + (bufoff) + ldsw + _i * 8192), 16, 0, 0); } while (0)
; #define PG8_LDA(dst, b, h) do { _Pragma("unroll") for (int m = 0; m < 4; ++m) _Pragma("unroll") for (int k = 0; k < 2; ++k) dst[m][k] = *(const PG8_LAS bf16x8*)(lds + PG8_SA(b, h) + aoff + m * 2048 + k * 1024); } while (0)
; #define PG8_MMA(ai, bj, At, Bt) do { __builtin_amdgcn_s_setprio(1); _Pragma("unroll") for (int m = 0; m < 4; ++m) _Pragma("unroll") for (int n = 0; n < 2; ++n) _Pragma("unroll") for (int k = 0; k < 2; ++k) \
;         acc[ai][bj][m][n] = __builtin_amdgcn_mfma_f32_16x16x32_bf16(Bt[n][k], At[m][k], acc[ai][bj][m][n], 0, 0, 0); __builtin_amdgcn_s_setprio(0); } while (0)
; #define PG8_WAIT_V(n) asm volatile("s_waitcnt vmcnt(" #n ")" ::: "memory")
; #define PG8_WAIT_L(n) asm volatile("s_waitcnt lgkmcnt(" #n ")" ::: "memory")
; #define PG8_BAR __builtin_amdgcn_s_barrier()
; #define PG8_SCHED __builtin_amdgcn_sched_barrier(0)
; template <class Epi, class Sched, bool ALIGN_EPI = false, bool SP2 = false>
; __device__ __forceinline__ void gemm_phase(PG8_LAS unsigned char* lds, const Gemm g, const Sched& S, const Epi& E) {
;     ...
;             PG8_WAIT_V(8); PG8_WAIT_L(0); PG8_BAR; PG8_MMA(0, 0, At, B0); PG8_MMA(0, 1, At, B1); PG8_BAR; PG8_SCHED;
;             PG8_LDA(At, 1, 1); PG8_STAGE(PG8_SB(1, 0), b3, voffB); PG8_STAGE(PG8_SB(1, 1), b3 + hstep, voffB); PG8_STAGE(PG8_SA(1, 0), a3, voffA);
;             PG8_WAIT_V(8); PG8_WAIT_L(0); PG8_BAR; PG8_MMA(1, 0, At, B0); PG8_MMA(1, 1, At, B1); PG8_BAR; PG8_SCHED;
	s_setprio 0
	s_add_i32 s24, s68, s9
	s_nop 2
	v_lshl_add_u64 v[82:83], v[170:171], 0, s[96:97]
	s_mov_b32 m0, s24
	ds_read_b128 v[196:199], v222 offset:49152
	ds_read_b128 v[200:203], v222 offset:50176
	ds_read_b128 v[204:207], v222 offset:51200
	ds_read_b128 v[224:227], v222 offset:52224
	ds_read_b128 v[228:231], v222 offset:53248
	ds_read_b128 v[232:235], v222 offset:54272
	ds_read_b128 v[236:239], v222 offset:55296
	ds_read_b128 v[240:243], v222 offset:56320
	global_load_lds_dwordx4 v[82:83], off
	s_add_i32 m0, s24, 0x2000
	s_add_u32 s22, s22, 0x100080
	v_lshl_add_u64 v[82:83], v[208:209], 0, s[96:97]
	s_addc_u32 s23, s23, 0
	s_add_i32 s24, s69, s9
	global_load_lds_dwordx4 v[82:83], off
	v_lshl_add_u64 v[82:83], s[22:23], 0, v[158:159]
	s_mov_b32 m0, s24
	s_nop 0
	global_load_lds_dwordx4 v[82:83], off
	v_lshl_add_u64 v[82:83], s[22:23], 0, v[172:173]
	s_add_i32 m0, s24, 0x2000
	s_nop 0
	global_load_lds_dwordx4 v[82:83], off
	v_lshl_add_u64 v[82:83], v[210:211], 0, s[96:97]
	s_mov_b32 m0, s0
	s_nop 0
	global_load_lds_dwordx4 v[82:83], off
	v_lshl_add_u64 v[82:83], v[244:245], 0, s[96:97]
	s_mov_b32 m0, s34
	s_nop 0
	global_load_lds_dwordx4 v[82:83], off
	s_waitcnt vmcnt(8)
	s_waitcnt lgkmcnt(0)
	s_setprio 1
	s_barrier
	v_mfma_f32_16x16x32_bf16 v[62:65], v[66:69], v[196:199], v[62:65]
	v_mfma_f32_16x16x32_bf16 v[42:45], v[74:77], v[196:199], v[42:45]
	v_mfma_f32_16x16x32_bf16 v[58:61], v[66:69], v[204:207], v[58:61]
	v_mfma_f32_16x16x32_bf16 v[38:41], v[74:77], v[204:207], v[38:41]
	v_mfma_f32_16x16x32_bf16 v[30:33], v[66:69], v[228:231], v[30:33]
	v_mfma_f32_16x16x32_bf16 v[22:25], v[74:77], v[228:231], v[22:25]
	v_mfma_f32_16x16x32_bf16 v[10:13], v[66:69], v[236:239], v[10:13]
	v_mfma_f32_16x16x32_bf16 v[6:9], v[74:77], v[236:239], v[6:9]
	v_mfma_f32_16x16x32_bf16 v[62:65], v[70:73], v[200:203], v[62:65]
	v_mfma_f32_16x16x32_bf16 v[42:45], v[78:81], v[200:203], v[42:45]
	v_mfma_f32_16x16x32_bf16 v[58:61], v[70:73], v[224:227], v[58:61]
	v_mfma_f32_16x16x32_bf16 v[38:41], v[78:81], v[224:227], v[38:41]
	v_mfma_f32_16x16x32_bf16 v[30:33], v[70:73], v[232:235], v[30:33]
	v_mfma_f32_16x16x32_bf16 v[22:25], v[78:81], v[232:235], v[22:25]
	v_mfma_f32_16x16x32_bf16 v[10:13], v[70:73], v[240:243], v[10:13]
	v_mfma_f32_16x16x32_bf16 v[6:9], v[78:81], v[240:243], v[6:9]
	v_mfma_f32_16x16x32_bf16 v[50:53], v[86:89], v[196:199], v[50:53]
	v_mfma_f32_16x16x32_bf16 v[82:85], v[154:157], v[200:203], v[50:53]
	v_mfma_f32_16x16x32_bf16 v[50:53], v[188:191], v[196:199], v[54:57]
	v_mfma_f32_16x16x32_bf16 v[46:49], v[86:89], v[204:207], v[46:49]
	v_mfma_f32_16x16x32_bf16 v[34:37], v[188:191], v[204:207], v[34:37]
	v_mfma_f32_16x16x32_bf16 v[26:29], v[86:89], v[228:231], v[26:29]
	v_mfma_f32_16x16x32_bf16 v[18:21], v[188:191], v[228:231], v[18:21]
	v_mfma_f32_16x16x32_bf16 v[14:17], v[86:89], v[236:239], v[14:17]
	v_mfma_f32_16x16x32_bf16 v[2:5], v[188:191], v[236:239], v[2:5]
	v_mfma_f32_16x16x32_bf16 v[78:81], v[192:195], v[200:203], v[50:53]
	v_mfma_f32_16x16x32_bf16 v[46:49], v[154:157], v[224:227], v[46:49]
	v_mfma_f32_16x16x32_bf16 v[34:37], v[192:195], v[224:227], v[34:37]
	v_mfma_f32_16x16x32_bf16 v[26:29], v[154:157], v[232:235], v[26:29]
	v_mfma_f32_16x16x32_bf16 v[18:21], v[192:195], v[232:235], v[18:21]
	v_mfma_f32_16x16x32_bf16 v[14:17], v[154:157], v[240:243], v[14:17]
	v_mfma_f32_16x16x32_bf16 v[2:5], v[192:195], v[240:243], v[2:5]
	s_barrier
	s_setprio 0
	s_add_i32 s65, s65, 2
	s_add_u32 s16, s16, 0x100
	s_addc_u32 s17, s17, 0
	s_add_u32 vcc_lo, vcc_lo, 0x100
	s_addc_u32 vcc_hi, vcc_hi, 0
	s_cmp_gt_u32 s65, 61
	s_cbranch_scc0 .LBB0_710
	s_and_b64 vcc, exec, s[54:55]
	s_cbranch_vccz .LBB0_713
	s_barrier

; #define PG8_STAGE(bufoff, gbase, voff) do { _Pragma("unroll") for (int _i = 0; _i < 2; ++_i) \
;         __builtin_amdgcn_global_load_lds((const unsigned*)((const char*)(gbase) + (voff)[_i]), (PG8_LAS unsigned*)(lds + (bufoff) + ldsw + _i * 8192), 16, 0, 0); } while (0)
; #define PG8_LDA(dst, b, h) do { _Pragma("unroll") for (int m = 0; m < 4; ++m) _Pragma("unroll") for (int k = 0; k < 2; ++k) dst[m][k] = *(const PG8_LAS bf16x8*)(lds + PG8_SA(b, h) + aoff + m * 2048 + k * 1024); } while (0)
; #define PG8_LDB(dst, b, h) do { _Pragma("unroll") for (int n = 0; n < 2; ++n) _Pragma("unroll") for (int k = 0; k < 2; ++k) dst[n][k] = *(const PG8_LAS bf16x8*)(lds + PG8_SB(b, h) + boff + n * 2048 + k * 1024); } while (0)
; #define PG8_MMA(ai, bj, At, Bt) do { __builtin_amdgcn_s_setprio(1); _Pragma("unroll") for (int m = 0; m < 4; ++m) _Pragma("unroll") for (int n = 0; n < 2; ++n) _Pragma("unroll") for (int k = 0; k < 2; ++k) \
;         acc[ai][bj][m][n] = __builtin_amdgcn_mfma_f32_16x16x32_bf16(Bt[n][k], At[m][k], acc[ai][bj][m][n], 0, 0, 0); __builtin_amdgcn_s_setprio(0); } while (0)
; #define PG8_WAIT_V(n) asm volatile("s_waitcnt vmcnt(" #n ")" ::: "memory")
; #define PG8_BAR __builtin_amdgcn_s_barrier()
; template <class Epi, class Sched, bool ALIGN_EPI = false, bool SP2 = false>
; __device__ __forceinline__ void gemm_phase(PG8_LAS unsigned char* lds, const Gemm g, const Sched& S, const Epi& E) {
;     ...
;         for (int t = 0; t < nt; t += 2) {
;             const bool last = (t == nt - 2);
;             const char* a1 = cA + (size_t)(t + 1) * kstep;
;             const char* a2 = last ? nA : cA + (size_t)(t + 2) * kstep; const char* b2 = last ? nB : cB + (size_t)(t + 2) * kstep;
;             const char* a3 = a2 + kstep; const char* b3 = b2 + kstep;
;             if (last && has_next) S.a_ready(nxt);
;             if constexpr (SP2) {
;             PG8_LDB(B0, 0, 0); PG8_LDB(B1, 0, 1); PG8_SCHED; PG8_LDA(At, 0, 0); PG8_STAGE(PG8_SA(1, 1), a1 + hstep, voffA);
;             PG8_WAIT_V(8); PG8_WAIT_L(0); PG8_BAR; PG8_MMA(0, 0, At, B0); PG8_MMA(0, 1, At, B1); PG8_BAR; PG8_SCHED;
;             PG8_LDA(At, 0, 1); PG8_STAGE(PG8_SB(0, 0), b2, voffB); PG8_STAGE(PG8_SB(0, 1), b2 + hstep, voffB); PG8_STAGE(PG8_SA(0, 0), a2, voffA);
;             PG8_WAIT_V(8); PG8_WAIT_L(0); PG8_BAR; PG8_MMA(1, 0, At, B0); PG8_MMA(1, 1, At, B1); PG8_BAR; PG8_SCHED;
.LBB0_915:
	s_add_i32 s30, s28, 2
	s_add_u32 s26, s48, 0x100
	s_addc_u32 s27, s49, 0
	s_add_i32 s43, 0, 0x10000
	s_cmp_eq_u32 s15, s28
	s_cselect_b32 s51, s45, s27
	s_cselect_b32 s50, s44, s26
	s_cselect_b32 s29, s47, s17
	s_cselect_b32 s28, s46, s16
	s_add_i32 s59, 0, 0x14000
	v_add_u32_e32 v142, s43, v188
	v_add_u32_e32 v170, s59, v188
	ds_read_b128 v[130:133], v142
	ds_read_b128 v[134:137], v142 offset:1024
	ds_read_b128 v[138:141], v142 offset:2048
	ds_read_b128 v[142:145], v142 offset:3072
	ds_read_b128 v[146:149], v170
	ds_read_b128 v[150:153], v170 offset:1024
	ds_read_b128 v[178:181], v170 offset:2048
	ds_read_b128 v[182:185], v170 offset:3072
	v_lshl_add_u64 v[170:171], s[48:49], 0, v[176:177]
	s_add_i32 m0, s9, 0xc000
	ds_read_b128 v[192:195], v190
	ds_read_b128 v[196:199], v190 offset:1024
	ds_read_b128 v[200:203], v190 offset:2048
	ds_read_b128 v[204:207], v190 offset:3072
	ds_read_b128 v[220:223], v190 offset:4096
	ds_read_b128 v[224:227], v190 offset:5120
	ds_read_b128 v[228:231], v190 offset:6144
	ds_read_b128 v[232:235], v190 offset:7168
	global_load_lds_dwordx4 v[170:171], off
	v_lshl_add_u64 v[170:171], s[48:49], 0, v[174:175]
	s_add_i32 m0, s9, 0xe000
	s_nop 0
	global_load_lds_dwordx4 v[170:171], off
	s_waitcnt vmcnt(8)
	s_waitcnt lgkmcnt(0)
	s_nop 0
	s_setprio 1
	s_barrier
	v_mfma_f32_16x16x32_bf16 v[126:129], v[130:133], v[192:195], v[126:129]
	v_mfma_f32_16x16x32_bf16 v[122:125], v[138:141], v[192:195], v[122:125]
	v_mfma_f32_16x16x32_bf16 v[118:121], v[130:133], v[200:203], v[118:121]
	v_mfma_f32_16x16x32_bf16 v[114:117], v[138:141], v[200:203], v[114:117]
	v_mfma_f32_16x16x32_bf16 v[102:105], v[130:133], v[220:223], v[102:105]
	v_mfma_f32_16x16x32_bf16 v[94:97], v[138:141], v[220:223], v[94:97]
	v_mfma_f32_16x16x32_bf16 v[86:89], v[130:133], v[228:231], v[86:89]
	v_mfma_f32_16x16x32_bf16 v[78:81], v[138:141], v[228:231], v[78:81]
	v_mfma_f32_16x16x32_bf16 v[126:129], v[134:137], v[196:199], v[126:129]
	v_mfma_f32_16x16x32_bf16 v[122:125], v[142:145], v[196:199], v[122:125]
	v_mfma_f32_16x16x32_bf16 v[118:121], v[134:137], v[204:207], v[118:121]
	v_mfma_f32_16x16x32_bf16 v[114:117], v[142:145], v[204:207], v[114:117]
	v_mfma_f32_16x16x32_bf16 v[102:105], v[134:137], v[224:227], v[102:105]
	v_mfma_f32_16x16x32_bf16 v[94:97], v[142:145], v[224:227], v[94:97]
	v_mfma_f32_16x16x32_bf16 v[86:89], v[134:137], v[232:235], v[86:89]
	v_mfma_f32_16x16x32_bf16 v[78:81], v[142:145], v[232:235], v[78:81]
	v_mfma_f32_16x16x32_bf16 v[110:113], v[146:149], v[192:195], v[110:113]
	v_mfma_f32_16x16x32_bf16 v[106:109], v[178:181], v[192:195], v[106:109]
	v_mfma_f32_16x16x32_bf16 v[98:101], v[146:149], v[200:203], v[98:101]
	v_mfma_f32_16x16x32_bf16 v[90:93], v[178:181], v[200:203], v[90:93]
	v_mfma_f32_16x16x32_bf16 v[82:85], v[146:149], v[220:223], v[82:85]
	v_mfma_f32_16x16x32_bf16 v[74:77], v[178:181], v[220:223], v[74:77]
	v_mfma_f32_16x16x32_bf16 v[70:73], v[146:149], v[228:231], v[70:73]
	v_mfma_f32_16x16x32_bf16 v[66:69], v[178:181], v[228:231], v[66:69]
	v_mfma_f32_16x16x32_bf16 v[110:113], v[150:153], v[196:199], v[110:113]
	v_mfma_f32_16x16x32_bf16 v[106:109], v[182:185], v[196:199], v[106:109]
	v_mfma_f32_16x16x32_bf16 v[98:101], v[150:153], v[204:207], v[98:101]
	v_mfma_f32_16x16x32_bf16 v[90:93], v[182:185], v[204:207], v[90:93]
	v_mfma_f32_16x16x32_bf16 v[82:85], v[150:153], v[224:227], v[82:85]
	v_mfma_f32_16x16x32_bf16 v[74:77], v[182:185], v[224:227], v[74:77]
	v_mfma_f32_16x16x32_bf16 v[70:73], v[150:153], v[232:235], v[70:73]
	v_mfma_f32_16x16x32_bf16 v[66:69], v[182:185], v[232:235], v[66:69]
	s_barrier
	s_setprio 0
	s_add_i32 s43, s43, s8
	v_lshl_add_u64 v[170:171], s[28:29], 0, v[158:159]
	s_mov_b32 m0, s43
	ds_read_b128 v[192:195], v190 offset:16384
	ds_read_b128 v[196:199], v190 offset:17408
	ds_read_b128 v[200:203], v190 offset:18432
	ds_read_b128 v[204:207], v190 offset:19456
	ds_read_b128 v[220:223], v190 offset:20480
	ds_read_b128 v[224:227], v190 offset:21504
	ds_read_b128 v[228:231], v190 offset:22528
	ds_read_b128 v[232:235], v190 offset:23552
	global_load_lds_dwordx4 v[170:171], off
	s_add_i32 m0, s43, 0x2000
	s_add_u32 s48, s28, 0x2b0000
	v_lshl_add_u64 v[186:187], s[28:29], 0, v[172:173]
	s_addc_u32 s49, s29, 0
	s_add_i32 s43, s59, s8
	global_load_lds_dwordx4 v[186:187], off
	v_lshl_add_u64 v[208:209], s[48:49], 0, v[158:159]
	s_mov_b32 m0, s43
	v_lshl_add_u64 v[210:211], s[50:51], 0, v[156:157]
	global_load_lds_dwordx4 v[208:209], off
	v_lshl_add_u64 v[208:209], s[48:49], 0, v[172:173]
	s_add_i32 m0, s43, 0x2000
	s_nop 0
	global_load_lds_dwordx4 v[208:209], off
	v_lshl_add_u64 v[208:209], s[50:51], 0, v[154:155]
	s_mov_b32 m0, s9
	s_nop 0
	global_load_lds_dwordx4 v[208:209], off
	s_mov_b32 m0, s10
	s_nop 0
	global_load_lds_dwordx4 v[210:211], off
	s_waitcnt vmcnt(8)
	s_waitcnt lgkmcnt(0)
	s_setprio 1
	s_barrier
; #define PG8_STAGE(bufoff, gbase, voff) do { _Pragma("unroll") for (int _i = 0; _i < 2; ++_i) \
;         __builtin_amdgcn_global_load_lds((const unsigned*)((const char*)(gbase) + (voff)[_i]), (PG8_LAS unsigned*)(lds + (bufoff) + ldsw + _i * 8192), 16, 0, 0); } while (0)
; #define PG8_LDA(dst, b, h) do { _Pragma("unroll") for (int m = 0; m < 4; ++m) _Pragma("unroll") for (int k = 0; k < 2; ++k) dst[m][k] = *(const PG8_LAS bf16x8*)(lds + PG8_SA(b, h) + aoff + m * 2048 + k * 1024); } while (0)
; #define PG8_LDB(dst, b, h) do { _Pragma("unroll") for (int n = 0; n < 2; ++n) _Pragma("unroll") for (int k = 0; k < 2; ++k) dst[n][k] = *(const PG8_LAS bf16x8*)(lds + PG8_SB(b, h) + boff + n * 2048 + k * 1024); } while (0)
; #define PG8_MMA(ai, bj, At, Bt) do { __builtin_amdgcn_s_setprio(1); _Pragma("unroll") for (int m = 0; m < 4; ++m) _Pragma("unroll") for (int n = 0; n < 2; ++n) _Pragma("unroll") for (int k = 0; k < 2; ++k) \
;         acc[ai][bj][m][n] = __builtin_amdgcn_mfma_f32_16x16x32_bf16(Bt[n][k], At[m][k], acc[ai][bj][m][n], 0, 0, 0); __builtin_amdgcn_s_setprio(0); } while (0)
; #define PG8_WAIT_V(n) asm volatile("s_waitcnt vmcnt(" #n ")" ::: "memory")
; #define PG8_WAIT_L(n) asm volatile("s_waitcnt lgkmcnt(" #n ")" ::: "memory")
; #define PG8_BAR __builtin_amdgcn_s_barrier()
; #define PG8_SCHED __builtin_amdgcn_sched_barrier(0)
; template <class Epi, class Sched, bool ALIGN_EPI = false, bool SP2 = false>
; __device__ __forceinline__ void gemm_phase(PG8_LAS unsigned char* lds, const Gemm g, const Sched& S, const Epi& E) {
;     ...
;             PG8_WAIT_V(8); PG8_WAIT_L(0); PG8_BAR; PG8_MMA(1, 0, At, B0); PG8_MMA(1, 1, At, B1); PG8_BAR; PG8_SCHED;
;             PG8_LDB(B0, 1, 0); PG8_LDB(B1, 1, 1); PG8_SCHED; PG8_LDA(At, 1, 0); PG8_STAGE(PG8_SA(0, 1), a2 + hstep, voffA);
;             PG8_WAIT_V(8); PG8_WAIT_L(0); PG8_BAR; PG8_MMA(0, 0, At, B0); PG8_MMA(0, 1, At, B1); PG8_BAR; PG8_SCHED;
	v_mfma_f32_16x16x32_bf16 v[62:65], v[130:133], v[192:195], v[62:65]
	v_mfma_f32_16x16x32_bf16 v[58:61], v[138:141], v[192:195], v[58:61]
	v_mfma_f32_16x16x32_bf16 v[54:57], v[130:133], v[200:203], v[54:57]
	v_mfma_f32_16x16x32_bf16 v[46:49], v[138:141], v[200:203], v[46:49]
	v_mfma_f32_16x16x32_bf16 v[38:41], v[130:133], v[220:223], v[38:41]
	v_mfma_f32_16x16x32_bf16 v[30:33], v[138:141], v[220:223], v[30:33]
	v_mfma_f32_16x16x32_bf16 v[22:25], v[130:133], v[228:231], v[22:25]
	v_mfma_f32_16x16x32_bf16 v[14:17], v[138:141], v[228:231], v[14:17]
	v_mfma_f32_16x16x32_bf16 v[62:65], v[134:137], v[196:199], v[62:65]
	v_mfma_f32_16x16x32_bf16 v[58:61], v[142:145], v[196:199], v[58:61]
	v_mfma_f32_16x16x32_bf16 v[54:57], v[134:137], v[204:207], v[54:57]
	v_mfma_f32_16x16x32_bf16 v[46:49], v[142:145], v[204:207], v[46:49]
	v_mfma_f32_16x16x32_bf16 v[38:41], v[134:137], v[224:227], v[38:41]
	v_mfma_f32_16x16x32_bf16 v[30:33], v[142:145], v[224:227], v[30:33]
	v_mfma_f32_16x16x32_bf16 v[22:25], v[134:137], v[232:235], v[22:25]
	v_mfma_f32_16x16x32_bf16 v[14:17], v[142:145], v[232:235], v[14:17]
	v_mfma_f32_16x16x32_bf16 v[50:53], v[146:149], v[192:195], v[50:53]
	v_mfma_f32_16x16x32_bf16 v[42:45], v[178:181], v[192:195], v[42:45]
	v_mfma_f32_16x16x32_bf16 v[34:37], v[146:149], v[200:203], v[34:37]
	v_mfma_f32_16x16x32_bf16 v[26:29], v[178:181], v[200:203], v[26:29]
	v_mfma_f32_16x16x32_bf16 v[18:21], v[146:149], v[220:223], v[18:21]
	v_mfma_f32_16x16x32_bf16 v[10:13], v[178:181], v[220:223], v[10:13]
	v_mfma_f32_16x16x32_bf16 v[6:9], v[146:149], v[228:231], v[6:9]
	v_mfma_f32_16x16x32_bf16 v[2:5], v[178:181], v[228:231], v[2:5]
	v_mfma_f32_16x16x32_bf16 v[50:53], v[150:153], v[196:199], v[50:53]
	v_mfma_f32_16x16x32_bf16 v[42:45], v[182:185], v[196:199], v[42:45]
	v_mfma_f32_16x16x32_bf16 v[34:37], v[150:153], v[204:207], v[34:37]
	v_mfma_f32_16x16x32_bf16 v[26:29], v[182:185], v[204:207], v[26:29]
	v_mfma_f32_16x16x32_bf16 v[18:21], v[150:153], v[224:227], v[18:21]
	v_mfma_f32_16x16x32_bf16 v[10:13], v[182:185], v[224:227], v[10:13]
	v_mfma_f32_16x16x32_bf16 v[6:9], v[150:153], v[232:235], v[6:9]
	v_mfma_f32_16x16x32_bf16 v[2:5], v[182:185], v[232:235], v[2:5]
	s_barrier
	s_setprio 0
	s_add_i32 s43, 0, 0x18000
	s_add_i32 s59, 0, 0x1c000
	v_add_u32_e32 v142, s43, v188
	v_add_u32_e32 v182, s59, v188
	ds_read_b128 v[130:133], v142
	ds_read_b128 v[134:137], v142 offset:1024
	ds_read_b128 v[138:141], v142 offset:2048
	ds_read_b128 v[142:145], v142 offset:3072
	ds_read_b128 v[146:149], v182
	ds_read_b128 v[150:153], v182 offset:1024
	ds_read_b128 v[178:181], v182 offset:2048
	ds_read_b128 v[182:185], v182 offset:3072
	s_add_u32 s48, s50, 0x2b0000
	s_addc_u32 s49, s51, 0
	s_mov_b32 m0, s11
	v_lshl_add_u64 v[236:237], s[48:49], 0, v[154:155]
	ds_read_b128 v[192:195], v190 offset:32768
	ds_read_b128 v[196:199], v190 offset:33792
	ds_read_b128 v[200:203], v190 offset:34816
	ds_read_b128 v[204:207], v190 offset:35840
	ds_read_b128 v[220:223], v190 offset:36864
	ds_read_b128 v[224:227], v190 offset:37888
	ds_read_b128 v[228:231], v190 offset:38912
	ds_read_b128 v[232:235], v190 offset:39936
	global_load_lds_dwordx4 v[236:237], off
	v_lshl_add_u64 v[236:237], s[48:49], 0, v[156:157]
	s_mov_b32 m0, s12
	s_nop 0
	global_load_lds_dwordx4 v[236:237], off
	s_waitcnt vmcnt(8)
	s_waitcnt lgkmcnt(0)
	s_setprio 1
	s_barrier
	v_mfma_f32_16x16x32_bf16 v[126:129], v[130:133], v[192:195], v[126:129]
	v_mfma_f32_16x16x32_bf16 v[122:125], v[138:141], v[192:195], v[122:125]
	v_mfma_f32_16x16x32_bf16 v[118:121], v[130:133], v[200:203], v[118:121]
	v_mfma_f32_16x16x32_bf16 v[114:117], v[138:141], v[200:203], v[114:117]
	v_mfma_f32_16x16x32_bf16 v[102:105], v[130:133], v[220:223], v[102:105]
	v_mfma_f32_16x16x32_bf16 v[94:97], v[138:141], v[220:223], v[94:97]
	v_mfma_f32_16x16x32_bf16 v[86:89], v[130:133], v[228:231], v[86:89]
	v_mfma_f32_16x16x32_bf16 v[78:81], v[138:141], v[228:231], v[78:81]
	v_mfma_f32_16x16x32_bf16 v[126:129], v[134:137], v[196:199], v[126:129]
	v_mfma_f32_16x16x32_bf16 v[122:125], v[142:145], v[196:199], v[122:125]
	v_mfma_f32_16x16x32_bf16 v[118:121], v[134:137], v[204:207], v[118:121]
	v_mfma_f32_16x16x32_bf16 v[114:117], v[142:145], v[204:207], v[114:117]
	v_mfma_f32_16x16x32_bf16 v[102:105], v[134:137], v[224:227], v[102:105]
	v_mfma_f32_16x16x32_bf16 v[94:97], v[142:145], v[224:227], v[94:97]
	v_mfma_f32_16x16x32_bf16 v[86:89], v[134:137], v[232:235], v[86:89]
	v_mfma_f32_16x16x32_bf16 v[78:81], v[142:145], v[232:235], v[78:81]
	v_mfma_f32_16x16x32_bf16 v[110:113], v[146:149], v[192:195], v[110:113]
	v_mfma_f32_16x16x32_bf16 v[106:109], v[178:181], v[192:195], v[106:109]
	v_mfma_f32_16x16x32_bf16 v[98:101], v[146:149], v[200:203], v[98:101]
	v_mfma_f32_16x16x32_bf16 v[90:93], v[178:181], v[200:203], v[90:93]
	v_mfma_f32_16x16x32_bf16 v[82:85], v[146:149], v[220:223], v[82:85]
	v_mfma_f32_16x16x32_bf16 v[74:77], v[178:181], v[220:223], v[74:77]
	v_mfma_f32_16x16x32_bf16 v[70:73], v[146:149], v[228:231], v[70:73]
	v_mfma_f32_16x16x32_bf16 v[66:69], v[178:181], v[228:231], v[66:69]
	v_mfma_f32_16x16x32_bf16 v[110:113], v[150:153], v[196:199], v[110:113]
	v_mfma_f32_16x16x32_bf16 v[106:109], v[182:185], v[196:199], v[106:109]
	v_mfma_f32_16x16x32_bf16 v[98:101], v[150:153], v[204:207], v[98:101]
	v_mfma_f32_16x16x32_bf16 v[90:93], v[182:185], v[204:207], v[90:93]
	v_mfma_f32_16x16x32_bf16 v[82:85], v[150:153], v[224:227], v[82:85]
	v_mfma_f32_16x16x32_bf16 v[74:77], v[182:185], v[224:227], v[74:77]
	v_mfma_f32_16x16x32_bf16 v[70:73], v[150:153], v[232:235], v[70:73]
	v_mfma_f32_16x16x32_bf16 v[66:69], v[182:185], v[232:235], v[66:69]
	s_barrier
; #define PG8_STAGE(bufoff, gbase, voff) do { _Pragma("unroll") for (int _i = 0; _i < 2; ++_i) \
;         __builtin_amdgcn_global_load_lds((const unsigned*)((const char*)(gbase) + (voff)[_i]), (PG8_LAS unsigned*)(lds + (bufoff) + ldsw + _i * 8192), 16, 0, 0); } while (0)
; #define PG8_LDA(dst, b, h) do { _Pragma("unroll") for (int m = 0; m < 4; ++m) _Pragma("unroll") for (int k = 0; k < 2; ++k) dst[m][k] = *(const PG8_LAS bf16x8*)(lds + PG8_SA(b, h) + aoff + m * 2048 + k * 1024); } while (0)
; #define PG8_MMA(ai, bj, At, Bt) do { __builtin_amdgcn_s_setprio(1); _Pragma("unroll") for (int m = 0; m < 4; ++m) _Pragma("unroll") for (int n = 0; n < 2; ++n) _Pragma("unroll") for (int k = 0; k < 2; ++k) \
;         acc[ai][bj][m][n] = __builtin_amdgcn_mfma_f32_16x16x32_bf16(Bt[n][k], At[m][k], acc[ai][bj][m][n], 0, 0, 0); __builtin_amdgcn_s_setprio(0); } while (0)
; #define PG8_WAIT_V(n) asm volatile("s_waitcnt vmcnt(" #n ")" ::: "memory")
; #define PG8_WAIT_L(n) asm volatile("s_waitcnt lgkmcnt(" #n ")" ::: "memory")
; #define PG8_BAR __builtin_amdgcn_s_barrier()
; #define PG8_SCHED __builtin_amdgcn_sched_barrier(0)
; template <class Epi, class Sched, bool ALIGN_EPI = false, bool SP2 = false>
; __device__ __forceinline__ void gemm_phase(PG8_LAS unsigned char* lds, const Gemm g, const Sched& S, const Epi& E) {
;     ...
;             PG8_LDA(At, 1, 1); PG8_STAGE(PG8_SB(1, 0), b3, voffB); PG8_STAGE(PG8_SB(1, 1), b3 + hstep, voffB); PG8_STAGE(PG8_SA(1, 0), a3, voffA);
;             PG8_WAIT_V(8); PG8_WAIT_L(0); PG8_BAR; PG8_MMA(1, 0, At, B0); PG8_MMA(1, 1, At, B1); PG8_BAR; PG8_SCHED;
	s_setprio 0
	s_add_i32 s43, s43, s8
	v_lshl_add_u64 v[170:171], v[170:171], 0, s[96:97]
	s_mov_b32 m0, s43
	ds_read_b128 v[192:195], v190 offset:49152
	ds_read_b128 v[196:199], v190 offset:50176
	ds_read_b128 v[200:203], v190 offset:51200
	ds_read_b128 v[204:207], v190 offset:52224
	ds_read_b128 v[220:223], v190 offset:53248
	ds_read_b128 v[224:227], v190 offset:54272
	ds_read_b128 v[228:231], v190 offset:55296
	ds_read_b128 v[232:235], v190 offset:56320
	global_load_lds_dwordx4 v[170:171], off
	s_add_i32 m0, s43, 0x2000
	s_add_u32 s28, s28, 0x2b0080
	v_lshl_add_u64 v[170:171], v[186:187], 0, s[96:97]
	s_addc_u32 s29, s29, 0
	s_add_i32 s43, s59, s8
	global_load_lds_dwordx4 v[170:171], off
	v_lshl_add_u64 v[170:171], s[28:29], 0, v[158:159]
	s_mov_b32 m0, s43
	s_nop 0
	global_load_lds_dwordx4 v[170:171], off
	v_lshl_add_u64 v[170:171], s[28:29], 0, v[172:173]
	s_add_i32 m0, s43, 0x2000
	s_nop 0
	global_load_lds_dwordx4 v[170:171], off
	v_lshl_add_u64 v[170:171], v[208:209], 0, s[96:97]
	s_mov_b32 m0, s35
	s_nop 0
	global_load_lds_dwordx4 v[170:171], off
	v_lshl_add_u64 v[170:171], v[210:211], 0, s[96:97]
	s_mov_b32 m0, s52
	s_nop 0
	global_load_lds_dwordx4 v[170:171], off
	s_waitcnt vmcnt(8)
	s_waitcnt lgkmcnt(0)
	s_nop 0
	s_setprio 1
	s_barrier
	v_mfma_f32_16x16x32_bf16 v[62:65], v[130:133], v[192:195], v[62:65]
	v_mfma_f32_16x16x32_bf16 v[58:61], v[138:141], v[192:195], v[58:61]
	v_mfma_f32_16x16x32_bf16 v[54:57], v[130:133], v[200:203], v[54:57]
	v_mfma_f32_16x16x32_bf16 v[46:49], v[138:141], v[200:203], v[46:49]
	v_mfma_f32_16x16x32_bf16 v[38:41], v[130:133], v[220:223], v[38:41]
	v_mfma_f32_16x16x32_bf16 v[30:33], v[138:141], v[220:223], v[30:33]
	v_mfma_f32_16x16x32_bf16 v[22:25], v[130:133], v[228:231], v[22:25]
	v_mfma_f32_16x16x32_bf16 v[14:17], v[138:141], v[228:231], v[14:17]
	v_mfma_f32_16x16x32_bf16 v[62:65], v[134:137], v[196:199], v[62:65]
	v_mfma_f32_16x16x32_bf16 v[58:61], v[142:145], v[196:199], v[58:61]
	v_mfma_f32_16x16x32_bf16 v[54:57], v[134:137], v[204:207], v[54:57]
	v_mfma_f32_16x16x32_bf16 v[46:49], v[142:145], v[204:207], v[46:49]
	v_mfma_f32_16x16x32_bf16 v[38:41], v[134:137], v[224:227], v[38:41]
	v_mfma_f32_16x16x32_bf16 v[30:33], v[142:145], v[224:227], v[30:33]
	v_mfma_f32_16x16x32_bf16 v[22:25], v[134:137], v[232:235], v[22:25]
	v_mfma_f32_16x16x32_bf16 v[14:17], v[142:145], v[232:235], v[14:17]
	v_mfma_f32_16x16x32_bf16 v[50:53], v[146:149], v[192:195], v[50:53]
	v_mfma_f32_16x16x32_bf16 v[42:45], v[178:181], v[192:195], v[42:45]
	v_mfma_f32_16x16x32_bf16 v[34:37], v[146:149], v[200:203], v[34:37]
	v_mfma_f32_16x16x32_bf16 v[26:29], v[178:181], v[200:203], v[26:29]
	v_mfma_f32_16x16x32_bf16 v[18:21], v[146:149], v[220:223], v[18:21]
	v_mfma_f32_16x16x32_bf16 v[10:13], v[178:181], v[220:223], v[10:13]
	v_mfma_f32_16x16x32_bf16 v[6:9], v[146:149], v[228:231], v[6:9]
	v_mfma_f32_16x16x32_bf16 v[2:5], v[178:181], v[228:231], v[2:5]
	v_mfma_f32_16x16x32_bf16 v[50:53], v[150:153], v[196:199], v[50:53]
	v_mfma_f32_16x16x32_bf16 v[42:45], v[182:185], v[196:199], v[42:45]
	v_mfma_f32_16x16x32_bf16 v[34:37], v[150:153], v[204:207], v[34:37]
	v_mfma_f32_16x16x32_bf16 v[26:29], v[182:185], v[204:207], v[26:29]
	v_mfma_f32_16x16x32_bf16 v[18:21], v[150:153], v[224:227], v[18:21]
	v_mfma_f32_16x16x32_bf16 v[10:13], v[182:185], v[224:227], v[10:13]
	v_mfma_f32_16x16x32_bf16 v[6:9], v[150:153], v[232:235], v[6:9]
	v_mfma_f32_16x16x32_bf16 v[2:5], v[182:185], v[232:235], v[2:5]
	s_barrier
	s_setprio 0
	s_add_u32 s16, s16, 0x100
	s_addc_u32 s17, s17, 0
	s_cmp_ge_i32 s30, s14
	s_mov_b64 s[48:49], s[26:27]
	s_mov_b32 s28, s30
	s_cbranch_scc0 .LBB0_915
	s_and_b64 vcc, exec, s[40:41]
	s_cbranch_vccz .LBB0_918
	s_barrier
